# scan phase: LDS reads of the GLA / GDN / SWA inner MFMA segments hoisted and renamed into free VGPRs, lgkmcnt waits re-derived
# speedup vs baseline: 1.0309x; 1.0020x over previous
; DI f32x4 mfma16(bf16x8 a, bf16x8 b, f32x4 c) { return __builtin_amdgcn_mfma_f32_16x16x32_bf16(a, b, c, 0, 0, 0); }
; DI void swa_item(const P& p, int l, int item, unsigned char* smem) {
;     ...
;         f32x4 sc[4];
; #pragma unroll
;         for (int kt = 0; kt < 4; ++kt) {
;             f32x4 acc = (f32x4){0.f, 0.f, 0.f, 0.f};
; #pragma unroll
;             for (int ks = 0; ks < 4; ++ks) acc = mfma16(ld8(sK + (16 * kt + l15) * 136 + 32 * ks + 8 * g), Qf[ks], acc);
;             sc[kt] = acc;
;         }
.LBB0_457:
	ds_read_b128 v[184:187], v117
	ds_read_b128 v[188:191], v117 offset:64
	ds_read_b128 v[192:195], v117 offset:4416
	ds_read_b128 v[196:199], v117 offset:8768
	ds_read_b128 v[200:203], v117 offset:13120
	ds_read_b128 v[204:207], v117 offset:128
	ds_read_b128 v[208:211], v117 offset:192
	ds_read_b128 v[212:215], v117 offset:4352
	ds_read_b128 v[216:219], v117 offset:4480
	ds_read_b128 v[224:227], v117 offset:4544
	ds_read_b128 v[228:231], v117 offset:8704
	ds_read_b128 v[232:235], v117 offset:8832
	s_add_i32 s0, s54, -3
	s_cmp_ge_i32 s0, s27
	s_waitcnt lgkmcnt(11)
	v_mfma_f32_16x16x32_bf16 v[80:83], v[184:187], v[56:59], 0
	ds_read_b128 v[236:239], v117 offset:8896
	s_waitcnt lgkmcnt(11)
	v_mfma_f32_16x16x32_bf16 v[80:83], v[188:191], v[60:63], v[80:83]
	ds_read_b128 v[240:243], v117 offset:13056
	s_waitcnt lgkmcnt(8)
	v_mfma_f32_16x16x32_bf16 v[80:83], v[204:207], v[72:75], v[80:83]
	ds_read_b128 v[244:247], v117 offset:13184
	ds_read_b128 v[248:251], v117 offset:13248
	s_waitcnt lgkmcnt(9)
	v_mfma_f32_16x16x32_bf16 v[80:83], v[208:211], v[76:79], v[80:83]
	s_waitcnt lgkmcnt(8)
	v_mfma_f32_16x16x32_bf16 v[84:87], v[212:215], v[56:59], 0
	v_mfma_f32_16x16x32_bf16 v[84:87], v[192:195], v[60:63], v[84:87]
	s_waitcnt lgkmcnt(7)
	v_mfma_f32_16x16x32_bf16 v[84:87], v[216:219], v[72:75], v[84:87]
	s_waitcnt lgkmcnt(6)
	v_mfma_f32_16x16x32_bf16 v[84:87], v[224:227], v[76:79], v[84:87]
	s_waitcnt lgkmcnt(5)
	v_mfma_f32_16x16x32_bf16 v[88:91], v[228:231], v[56:59], 0
	v_mfma_f32_16x16x32_bf16 v[88:91], v[196:199], v[60:63], v[88:91]
	s_waitcnt lgkmcnt(4)
	v_mfma_f32_16x16x32_bf16 v[88:91], v[232:235], v[72:75], v[88:91]
	s_waitcnt lgkmcnt(3)
	v_mfma_f32_16x16x32_bf16 v[88:91], v[236:239], v[76:79], v[88:91]
	s_waitcnt lgkmcnt(2)
	v_mfma_f32_16x16x32_bf16 v[92:95], v[240:243], v[56:59], 0
	v_mfma_f32_16x16x32_bf16 v[92:95], v[200:203], v[60:63], v[92:95]
	s_waitcnt lgkmcnt(1)
	v_mfma_f32_16x16x32_bf16 v[92:95], v[244:247], v[72:75], v[92:95]
	s_waitcnt lgkmcnt(0)
	v_mfma_f32_16x16x32_bf16 v[92:95], v[248:251], v[76:79], v[92:95]
	s_cbranch_scc1 .LBB0_460
	s_cmp_gt_i32 s2, s43
	s_cselect_b64 s[0:1], -1, 0
	s_cmp_lt_i32 s2, s48
	s_cselect_b64 s[4:5], -1, 0
	s_and_b64 s[0:1], s[0:1], s[4:5]
	s_and_b64 vcc, exec, s[0:1]
	s_cbranch_vccnz .LBB0_460
	v_add_u32_e32 v119, s49, v116
	v_add_u32_e32 v121, 0xffffff7f, v119
	v_cmp_gt_u32_e32 vcc, s6, v121
	v_mov_b32_e32 v122, s7
	v_add_u32_e32 v121, 0xffffff80, v119
	v_cndmask_b32_e32 v80, v80, v122, vcc
	v_cmp_lt_u32_e32 vcc, s8, v121
	v_add_u32_e32 v121, 0xffffff81, v119
	s_nop 0
	v_cndmask_b32_e32 v81, v180, v81, vcc
	v_cmp_lt_u32_e32 vcc, s8, v121
	v_add_u32_e32 v121, 0xffffff82, v119
	s_nop 0
	v_cndmask_b32_e32 v82, v180, v82, vcc
	v_cmp_lt_u32_e32 vcc, s8, v121
	v_add_u32_e32 v121, 0xffffff8f, v119
	s_nop 0
	v_cndmask_b32_e32 v83, v180, v83, vcc
	v_cmp_gt_u32_e32 vcc, s6, v121
	v_add_u32_e32 v121, 0xffffff90, v119
	s_nop 0
	v_cndmask_b32_e32 v84, v84, v122, vcc
	v_cmp_lt_u32_e32 vcc, s8, v121
	v_add_u32_e32 v121, 0xffffff91, v119
	s_nop 0
	v_cndmask_b32_e32 v85, v180, v85, vcc
	v_cmp_lt_u32_e32 vcc, s8, v121
	v_add_u32_e32 v121, 0xffffff92, v119
	s_nop 0
	v_cndmask_b32_e32 v86, v180, v86, vcc
	v_cmp_lt_u32_e32 vcc, s8, v121
	v_add_u32_e32 v121, 0xffffff9f, v119
	s_nop 0
	v_cndmask_b32_e32 v87, v180, v87, vcc
	v_cmp_gt_u32_e32 vcc, s6, v121
	v_add_u32_e32 v121, 0xffffffa0, v119
	s_nop 0
	v_cndmask_b32_e32 v88, v88, v122, vcc
	v_cmp_lt_u32_e32 vcc, s8, v121
	v_add_u32_e32 v121, 0xffffffa1, v119
	s_nop 0
	v_cndmask_b32_e32 v89, v180, v89, vcc
	v_cmp_lt_u32_e32 vcc, s8, v121
	v_add_u32_e32 v121, 0xffffffa2, v119
	s_nop 0
	v_cndmask_b32_e32 v90, v180, v90, vcc
	v_cmp_lt_u32_e32 vcc, s8, v121
	v_add_u32_e32 v121, 0xffffffaf, v119
	s_nop 0
	v_cndmask_b32_e32 v91, v180, v91, vcc
	v_cmp_gt_u32_e32 vcc, s6, v121
	v_add_u32_e32 v121, 0xffffffb0, v119
	s_nop 0
	v_cndmask_b32_e32 v92, v92, v122, vcc
	v_cmp_lt_u32_e32 vcc, s8, v121
	v_add_u32_e32 v121, 0xffffffb1, v119
	v_add_u32_e32 v119, 0xffffffb2, v119
	v_cndmask_b32_e32 v93, v180, v93, vcc
	v_cmp_lt_u32_e32 vcc, s8, v121
	s_nop 1
	v_cndmask_b32_e32 v94, v180, v94, vcc
	v_cmp_lt_u32_e32 vcc, s8, v119
	s_nop 1
	v_cndmask_b32_e32 v95, v180, v95, vcc
; DI bf16x8 tr2(const bf16_t* p0, const bf16_t* p1) { s16x4 a = trread(p0), b = trread(p1); return __builtin_shufflevector(a, b, 0, 1, 2, 3, 4, 5, 6, 7); }
; DI f32x4 mfma16(bf16x8 a, bf16x8 b, f32x4 c) { return __builtin_amdgcn_mfma_f32_16x16x32_bf16(a, b, c, 0, 0, 0); }
; DI void swa_item(const P& p, int l, int item, unsigned char* smem) {
;     ...
;         float tmax = -1e30f;
; #pragma unroll
;         for (int kt = 0; kt < 4; ++kt)
; #pragma unroll
;             for (int r = 0; r < 4; ++r) tmax = fmaxf(tmax, sc[kt][r]);
;         tmax = fmaxf(tmax, __shfl_xor(tmax, 16)); tmax = fmaxf(tmax, __shfl_xor(tmax, 32));
;         const float mn = fmaxf(m, tmax), alpha = __builtin_amdgcn_exp2f(m - mn);
;         m = mn;
;         float psum = 0.f;
; #pragma unroll
;         for (int kt = 0; kt < 4; ++kt)
; #pragma unroll
;             for (int r = 0; r < 4; ++r) { const float pv = __builtin_amdgcn_exp2f(sc[kt][r] - mn); sc[kt][r] = pv; psum += pv; }
;         lsum = lsum * alpha + psum;
;         bf16x8 Bp[2];
;         Bp[0] = packacc(sc[0], sc[1]); Bp[1] = packacc(sc[2], sc[3]);
; #pragma unroll
;         for (int nt = 0; nt < 8; ++nt) {
;             ot[nt] *= alpha;
; #pragma unroll
;             for (int k2 = 0; k2 < 2; ++k2) {
;                 const bf16x8 av = tr2(sV + (32 * k2 + 4 * g + q4) * 144 + 16 * nt + 4 * p4, sV + (32 * k2 + 16 + 4 * g + q4) * 144 + 16 * nt + 4 * p4);
;                 ot[nt] = mfma16(av, Bp[k2], ot[nt]);
;             }
;         }
.LBB0_460:
	v_max3_f32 v119, v80, s7, v81
	v_max3_f32 v119, v119, v82, v83
	v_max3_f32 v119, v119, v84, v85
	v_max3_f32 v119, v119, v86, v87
	v_max3_f32 v119, v119, v88, v89
	v_max3_f32 v119, v119, v90, v91
	s_nop 0
	v_max3_f32 v119, v119, v92, v93
	v_max3_f32 v119, v119, v94, v95
	ds_bpermute_b32 v121, v113, v119
	s_add_i32 s3, s54, -2
	s_cmp_ge_i32 s3, s42
	s_waitcnt lgkmcnt(0)
	v_max_f32_e32 v121, v121, v121
	v_max_f32_e32 v119, v119, v121
	ds_bpermute_b32 v121, v114, v119
	ds_read_b64_tr_b16 v[186:187], v115 offset:22016
	ds_read_b64_tr_b16 v[184:185], v115 offset:17408
	ds_read_b64_tr_b16 v[188:189], v115 offset:26624
	ds_read_b64_tr_b16 v[190:191], v115 offset:31232
	ds_read_b64_tr_b16 v[192:193], v115 offset:26656
	ds_read_b64_tr_b16 v[194:195], v115 offset:31264
	ds_read_b64_tr_b16 v[196:197], v115 offset:17472
	ds_read_b64_tr_b16 v[198:199], v115 offset:22080
	ds_read_b64_tr_b16 v[200:201], v115 offset:26688
	ds_read_b64_tr_b16 v[202:203], v115 offset:31296
	ds_read_b64_tr_b16 v[204:205], v115 offset:17504
	s_waitcnt lgkmcnt(11)
	v_max3_f32 v119, v118, v119, v121
	ds_read_b64_tr_b16 v[206:207], v115 offset:22112
	v_sub_f32_e32 v80, v80, v119
	v_exp_f32_e32 v80, v80
	v_sub_f32_e32 v81, v81, v119
	v_exp_f32_e32 v81, v81
	v_sub_f32_e32 v82, v82, v119
	v_exp_f32_e32 v82, v82
	v_sub_f32_e32 v83, v83, v119
	v_exp_f32_e32 v83, v83
	v_sub_f32_e32 v84, v84, v119
	v_sub_f32_e32 v121, v118, v119
	v_add_f32_e32 v118, 0, v80
	v_exp_f32_e32 v122, v84
	v_sub_f32_e32 v85, v85, v119
	v_add_f32_e32 v118, v81, v118
	v_exp_f32_e32 v123, v85
	v_sub_f32_e32 v85, v86, v119
	v_add_f32_e32 v118, v82, v118
	v_exp_f32_e32 v124, v85
	v_sub_f32_e32 v85, v87, v119
	v_add_f32_e32 v118, v83, v118
	v_exp_f32_e32 v87, v85
	v_sub_f32_e32 v85, v88, v119
	v_add_f32_e32 v84, v122, v118
	v_exp_f32_e32 v125, v85
	v_sub_f32_e32 v85, v89, v119
	v_add_f32_e32 v84, v123, v84
	v_exp_f32_e32 v89, v85
	v_sub_f32_e32 v85, v90, v119
	v_add_f32_e32 v84, v124, v84
	v_exp_f32_e32 v90, v85
	v_sub_f32_e32 v85, v91, v119
	v_add_f32_e32 v84, v87, v84
	v_exp_f32_e32 v91, v85
	v_sub_f32_e32 v85, v92, v119
	v_add_f32_e32 v84, v125, v84
	v_exp_f32_e32 v92, v85
	v_sub_f32_e32 v85, v93, v119
	v_add_f32_e32 v84, v89, v84
	v_exp_f32_e32 v93, v85
	v_sub_f32_e32 v85, v94, v119
	v_add_f32_e32 v84, v90, v84
	v_exp_f32_e32 v94, v85
	v_sub_f32_e32 v85, v95, v119
	v_add_f32_e32 v84, v91, v84
	v_exp_f32_e32 v95, v85
	v_add_f32_e32 v84, v92, v84
	v_exp_f32_e32 v88, v121
	v_add_f32_e32 v84, v93, v84
	v_add_f32_e32 v84, v94, v84
	v_add_f32_e32 v118, v95, v84
	v_fmac_f32_e32 v118, v120, v88
	v_cvt_pk_bf16_f32 v84, v80, v81
	v_cvt_pk_bf16_f32 v85, v82, v83
	v_cvt_pk_bf16_f32 v81, v90, v91
	v_cvt_pk_bf16_f32 v82, v92, v93
	ds_read_b64_tr_b16 v[120:121], v115 offset:17440
	v_cvt_pk_bf16_f32 v86, v122, v123
	v_cvt_pk_bf16_f32 v87, v124, v87
	v_pk_mul_f32 v[50:51], v[50:51], v[88:89] op_sel_hi:[1,0]
	v_pk_mul_f32 v[48:49], v[48:49], v[88:89] op_sel_hi:[1,0]
	v_cvt_pk_bf16_f32 v80, v125, v89
	v_cvt_pk_bf16_f32 v83, v94, v95
	s_waitcnt lgkmcnt(11)
	v_mfma_f32_16x16x32_bf16 v[48:51], v[184:187], v[84:87], v[48:51]
	ds_read_b64_tr_b16 v[122:123], v115 offset:22048
	v_pk_mul_f32 v[26:27], v[26:27], v[88:89] op_sel_hi:[1,0]
	s_waitcnt lgkmcnt(10)
	v_mfma_f32_16x16x32_bf16 v[48:51], v[188:191], v[80:83], v[48:51]
	ds_read_b64_tr_b16 v[208:209], v115 offset:26720
	ds_read_b64_tr_b16 v[210:211], v115 offset:31328
	v_mul_f32_e64 v24, v24, v88
	v_mul_f32_e64 v25, v25, v88
	v_pk_mul_f32 v[22:23], v[22:23], v[88:89] op_sel_hi:[1,0]
	s_waitcnt lgkmcnt(2)
	v_mfma_f32_16x16x32_bf16 v[24:27], v[120:123], v[84:87], v[24:27]
	ds_read_b64_tr_b16 v[212:213], v115 offset:17536
	ds_read_b64_tr_b16 v[214:215], v115 offset:22144
	ds_read_b64_tr_b16 v[216:217], v115 offset:26752
	ds_read_b64_tr_b16 v[218:219], v115 offset:31360
	ds_read_b64_tr_b16 v[224:225], v115 offset:17568
	ds_read_b64_tr_b16 v[226:227], v115 offset:22176
	ds_read_b64_tr_b16 v[228:229], v115 offset:26784
	ds_read_b64_tr_b16 v[230:231], v115 offset:31392
	ds_read_b64_tr_b16 v[232:233], v115 offset:17600
	ds_read_b64_tr_b16 v[234:235], v115 offset:22208
	v_mul_f32_e64 v20, v20, v88
	v_mul_f32_e64 v21, v21, v88
	v_pk_mul_f32 v[18:19], v[18:19], v[88:89] op_sel_hi:[1,0]
	v_pk_mul_f32 v[16:17], v[16:17], v[88:89] op_sel_hi:[1,0]
	v_mfma_f32_16x16x32_bf16 v[24:27], v[192:195], v[80:83], v[24:27]
	v_pk_mul_f32 v[14:15], v[14:15], v[88:89] op_sel_hi:[1,0]
	v_pk_mul_f32 v[12:13], v[12:13], v[88:89] op_sel_hi:[1,0]
	v_mfma_f32_16x16x32_bf16 v[20:23], v[196:199], v[84:87], v[20:23]
	v_pk_mul_f32 v[10:11], v[10:11], v[88:89] op_sel_hi:[1,0]
	v_pk_mul_f32 v[8:9], v[8:9], v[88:89] op_sel_hi:[1,0]
	v_mfma_f32_16x16x32_bf16 v[20:23], v[200:203], v[80:83], v[20:23]
	v_pk_mul_f32 v[6:7], v[6:7], v[88:89] op_sel_hi:[1,0]
	v_pk_mul_f32 v[4:5], v[4:5], v[88:89] op_sel_hi:[1,0]
	v_mfma_f32_16x16x32_bf16 v[16:19], v[204:207], v[84:87], v[16:19]
	v_pk_mul_f32 v[2:3], v[2:3], v[88:89] op_sel_hi:[1,0]
	v_pk_mul_f32 v[0:1], v[0:1], v[88:89] op_sel_hi:[1,0]
	s_waitcnt lgkmcnt(10)
	v_mfma_f32_16x16x32_bf16 v[16:19], v[208:211], v[80:83], v[16:19]
	ds_read_b64_tr_b16 v[236:237], v115 offset:26816
	ds_read_b64_tr_b16 v[238:239], v115 offset:31424
	s_waitcnt lgkmcnt(10)
	v_mfma_f32_16x16x32_bf16 v[12:15], v[212:215], v[84:87], v[12:15]
	ds_read_b64_tr_b16 v[88:89], v115 offset:17632
	ds_read_b64_tr_b16 v[90:91], v115 offset:22240
	s_waitcnt lgkmcnt(10)
	v_mfma_f32_16x16x32_bf16 v[12:15], v[216:219], v[80:83], v[12:15]
	ds_read_b64_tr_b16 v[240:241], v115 offset:26848
	ds_read_b64_tr_b16 v[242:243], v115 offset:31456
	s_waitcnt lgkmcnt(10)
	v_mfma_f32_16x16x32_bf16 v[8:11], v[224:227], v[84:87], v[8:11]
	s_waitcnt lgkmcnt(8)
	v_mfma_f32_16x16x32_bf16 v[8:11], v[228:231], v[80:83], v[8:11]
	s_waitcnt lgkmcnt(6)
	v_mfma_f32_16x16x32_bf16 v[4:7], v[232:235], v[84:87], v[4:7]
	s_waitcnt lgkmcnt(4)
	v_mfma_f32_16x16x32_bf16 v[4:7], v[236:239], v[80:83], v[4:7]
	s_waitcnt lgkmcnt(2)
	v_mfma_f32_16x16x32_bf16 v[0:3], v[88:91], v[84:87], v[0:3]
	s_waitcnt lgkmcnt(0)
	v_mfma_f32_16x16x32_bf16 v[0:3], v[240:243], v[80:83], v[0:3]
	s_cbranch_scc1 .LBB0_471
	s_cmp_ge_i32 s54, s42
	s_barrier
	ds_write_b128 v111, v[44:47]
	ds_write_b128 v111, v[52:55] offset:64
	ds_write_b128 v112, v[64:67] offset:17408
	ds_write_b128 v112, v[68:71] offset:17424
	s_waitcnt lgkmcnt(0)
	s_barrier
	s_cbranch_scc1 .LBB0_467
	s_add_i32 s1, s30, s49
	s_add_i32 s0, s2, 0xc0
	s_addk_i32 s1, 0xc0
	s_cmp_lt_i32 s54, s27
	s_cselect_b32 s0, s0, s1
	s_cselect_b32 s1, s22, s24
	s_add_i32 s0, s0, s1
	s_ashr_i32 s1, s0, 31
	s_cmp_ge_i32 s54, s27
	v_lshl_add_u64 v[44:45], s[0:1], 0, v[102:103]
	s_mov_b64 s[0:1], -1
	s_cbranch_scc0 .LBB0_464
	s_movk_i32 s4, 0x3800
	v_mov_b64_e32 v[46:47], s[40:41]
	v_mad_u64_u32 v[64:65], s[0:1], v44, s4, 0
	v_mad_u64_u32 v[46:47], s[0:1], v44, s4, v[46:47]
	v_mad_i32_i24 v47, v45, s4, v47
	s_mov_b64 s[0:1], 0x3000
	v_mad_i32_i24 v65, v45, s4, v65
	v_lshl_add_u64 v[46:47], v[46:47], 0, s[0:1]
	s_mov_b64 s[0:1], 0

; DI f32x4 mfma16(bf16x8 a, bf16x8 b, f32x4 c) { return __builtin_amdgcn_mfma_f32_16x16x32_bf16(a, b, c, 0, 0, 0); }
; DI void swa_item(const P& p, int l, int item, unsigned char* smem) {
;     ...
;         f32x4 sc[4];
; #pragma unroll
;         for (int kt = 0; kt < 4; ++kt) {
;             f32x4 acc = (f32x4){0.f, 0.f, 0.f, 0.f};
; #pragma unroll
;             for (int ks = 0; ks < 4; ++ks) acc = mfma16(ld8(sK + (16 * kt + l15) * 136 + 32 * ks + 8 * g), Qf[ks], acc);
;             sc[kt] = acc;
;         }
;         if (loc && (kpos0 <= 64 * qb - 128 || kpos0 >= 64 * qb + 128)) {
; #pragma unroll
;             for (int kt = 0; kt < 4; ++kt)
; #pragma unroll
;                 for (int r = 0; r < 4; ++r) { const int dd = kpos0 + 16 * kt + 4 * g + r - qpos; if (dd > 128 || dd < -128) sc[kt][r] = -1e30f; }
;         }
.LBB0_467:
	ds_read_b128 v[184:187], v117
	ds_read_b128 v[188:191], v117 offset:64
	ds_read_b128 v[192:195], v117 offset:4416
	ds_read_b128 v[196:199], v117 offset:8768
	ds_read_b128 v[200:203], v117 offset:13120
	ds_read_b128 v[204:207], v117 offset:128
	ds_read_b128 v[208:211], v117 offset:192
	ds_read_b128 v[212:215], v117 offset:4352
	ds_read_b128 v[216:219], v117 offset:4480
	ds_read_b128 v[224:227], v117 offset:4544
	ds_read_b128 v[228:231], v117 offset:8704
	ds_read_b128 v[232:235], v117 offset:8832
	s_cmp_ge_i32 s3, s27
	s_waitcnt lgkmcnt(11)
	v_mfma_f32_16x16x32_bf16 v[80:83], v[184:187], v[56:59], 0
	ds_read_b128 v[236:239], v117 offset:8896
	s_waitcnt lgkmcnt(11)
	v_mfma_f32_16x16x32_bf16 v[80:83], v[188:191], v[60:63], v[80:83]
	ds_read_b128 v[240:243], v117 offset:13056
	s_waitcnt lgkmcnt(8)
	v_mfma_f32_16x16x32_bf16 v[80:83], v[204:207], v[72:75], v[80:83]
	ds_read_b128 v[244:247], v117 offset:13184
	ds_read_b128 v[248:251], v117 offset:13248
	s_waitcnt lgkmcnt(9)
	v_mfma_f32_16x16x32_bf16 v[80:83], v[208:211], v[76:79], v[80:83]
	s_waitcnt lgkmcnt(8)
	v_mfma_f32_16x16x32_bf16 v[84:87], v[212:215], v[56:59], 0
	v_mfma_f32_16x16x32_bf16 v[84:87], v[192:195], v[60:63], v[84:87]
	s_waitcnt lgkmcnt(7)
	v_mfma_f32_16x16x32_bf16 v[84:87], v[216:219], v[72:75], v[84:87]
	s_waitcnt lgkmcnt(6)
	v_mfma_f32_16x16x32_bf16 v[84:87], v[224:227], v[76:79], v[84:87]
	s_waitcnt lgkmcnt(5)
	v_mfma_f32_16x16x32_bf16 v[88:91], v[228:231], v[56:59], 0
	v_mfma_f32_16x16x32_bf16 v[88:91], v[196:199], v[60:63], v[88:91]
	s_waitcnt lgkmcnt(4)
	v_mfma_f32_16x16x32_bf16 v[88:91], v[232:235], v[72:75], v[88:91]
	s_waitcnt lgkmcnt(3)
	v_mfma_f32_16x16x32_bf16 v[88:91], v[236:239], v[76:79], v[88:91]
	s_waitcnt lgkmcnt(2)
	v_mfma_f32_16x16x32_bf16 v[92:95], v[240:243], v[56:59], 0
	v_mfma_f32_16x16x32_bf16 v[92:95], v[200:203], v[60:63], v[92:95]
	s_waitcnt lgkmcnt(1)
	v_mfma_f32_16x16x32_bf16 v[92:95], v[244:247], v[72:75], v[92:95]
	s_waitcnt lgkmcnt(0)
	v_mfma_f32_16x16x32_bf16 v[92:95], v[248:251], v[76:79], v[92:95]
	s_cbranch_scc1 .LBB0_470
	s_add_i32 s2, s2, 64
	s_cmp_gt_i32 s2, s43
	s_cselect_b64 s[0:1], -1, 0
	s_cmp_lt_i32 s2, s48
	s_cselect_b64 s[2:3], -1, 0
	s_and_b64 s[0:1], s[0:1], s[2:3]
	s_and_b64 vcc, exec, s[0:1]
	s_cbranch_vccnz .LBB0_470
	v_add_u32_e32 v121, s49, v116
	v_add_u32_e32 v120, 0xffffffbf, v121
	v_cmp_gt_u32_e32 vcc, s6, v120
	v_mov_b32_e32 v120, s7
	s_nop 0
	v_cndmask_b32_e32 v80, v80, v120, vcc
	v_subrev_u32_e32 v120, 64, v121
	v_cmp_lt_u32_e32 vcc, s8, v120
	v_subrev_u32_e32 v120, 63, v121
	s_nop 0
	v_cndmask_b32_e32 v81, v180, v81, vcc
	v_cmp_lt_u32_e32 vcc, s8, v120
	v_subrev_u32_e32 v120, 62, v121
	s_nop 0
	v_cndmask_b32_e32 v82, v180, v82, vcc
	v_cmp_lt_u32_e32 vcc, s8, v120
	v_subrev_u32_e32 v120, 49, v121
	s_nop 0
	v_cndmask_b32_e32 v83, v180, v83, vcc
	v_cmp_gt_u32_e32 vcc, s6, v120
	v_mov_b32_e32 v120, s7
	s_nop 0
	v_cndmask_b32_e32 v84, v84, v120, vcc
	v_subrev_u32_e32 v120, 48, v121
	v_cmp_lt_u32_e32 vcc, s8, v120
	v_subrev_u32_e32 v120, 47, v121
	s_nop 0
	v_cndmask_b32_e32 v85, v180, v85, vcc
	v_cmp_lt_u32_e32 vcc, s8, v120
	v_subrev_u32_e32 v120, 46, v121
	s_nop 0
	v_cndmask_b32_e32 v86, v180, v86, vcc
	v_cmp_lt_u32_e32 vcc, s8, v120
	v_subrev_u32_e32 v120, 33, v121
	s_nop 0
	v_cndmask_b32_e32 v87, v180, v87, vcc
	v_cmp_gt_u32_e32 vcc, s6, v120
	v_mov_b32_e32 v120, s7
	s_nop 0
	v_cndmask_b32_e32 v88, v88, v120, vcc
	v_subrev_u32_e32 v120, 32, v121
	v_cmp_lt_u32_e32 vcc, s8, v120
	v_subrev_u32_e32 v120, 31, v121
	s_nop 0
	v_cndmask_b32_e32 v89, v180, v89, vcc
	v_cmp_lt_u32_e32 vcc, s8, v120
	v_subrev_u32_e32 v120, 30, v121
	s_nop 0
	v_cndmask_b32_e32 v90, v180, v90, vcc
	v_cmp_lt_u32_e32 vcc, s8, v120
	v_subrev_u32_e32 v120, 17, v121
	s_nop 0
	v_cndmask_b32_e32 v91, v180, v91, vcc
	v_cmp_gt_u32_e32 vcc, s6, v120
	v_mov_b32_e32 v120, s7
	s_nop 0
	v_cndmask_b32_e32 v92, v92, v120, vcc
	v_add_u32_e32 v120, -16, v121
	v_cmp_lt_u32_e32 vcc, s8, v120
	v_add_u32_e32 v120, -15, v121
	s_nop 0
	v_cndmask_b32_e32 v93, v180, v93, vcc
	v_cmp_lt_u32_e32 vcc, s8, v120
	v_add_u32_e32 v120, -14, v121
	s_nop 0
	v_cndmask_b32_e32 v94, v180, v94, vcc
	v_cmp_lt_u32_e32 vcc, s8, v120
	s_nop 1
	v_cndmask_b32_e32 v95, v180, v95, vcc
; DI bf16x8 tr2(const bf16_t* p0, const bf16_t* p1) { s16x4 a = trread(p0), b = trread(p1); return __builtin_shufflevector(a, b, 0, 1, 2, 3, 4, 5, 6, 7); }
; DI f32x4 mfma16(bf16x8 a, bf16x8 b, f32x4 c) { return __builtin_amdgcn_mfma_f32_16x16x32_bf16(a, b, c, 0, 0, 0); }
; DI void swa_item(const P& p, int l, int item, unsigned char* smem) {
;     ...
;         float tmax = -1e30f;
; #pragma unroll
;         for (int kt = 0; kt < 4; ++kt)
; #pragma unroll
;             for (int r = 0; r < 4; ++r) tmax = fmaxf(tmax, sc[kt][r]);
;         tmax = fmaxf(tmax, __shfl_xor(tmax, 16)); tmax = fmaxf(tmax, __shfl_xor(tmax, 32));
;         const float mn = fmaxf(m, tmax), alpha = __builtin_amdgcn_exp2f(m - mn);
;         m = mn;
;         float psum = 0.f;
; #pragma unroll
;         for (int kt = 0; kt < 4; ++kt)
; #pragma unroll
;             for (int r = 0; r < 4; ++r) { const float pv = __builtin_amdgcn_exp2f(sc[kt][r] - mn); sc[kt][r] = pv; psum += pv; }
;         lsum = lsum * alpha + psum;
;         bf16x8 Bp[2];
;         Bp[0] = packacc(sc[0], sc[1]); Bp[1] = packacc(sc[2], sc[3]);
; #pragma unroll
;         for (int nt = 0; nt < 8; ++nt) {
;             ot[nt] *= alpha;
; #pragma unroll
;             for (int k2 = 0; k2 < 2; ++k2) {
;                 const bf16x8 av = tr2(sV + (32 * k2 + 4 * g + q4) * 144 + 16 * nt + 4 * p4, sV + (32 * k2 + 16 + 4 * g + q4) * 144 + 16 * nt + 4 * p4);
;                 ot[nt] = mfma16(av, Bp[k2], ot[nt]);
;             }
;         }
.LBB0_470:
	v_max3_f32 v120, v80, s7, v81
	v_max3_f32 v120, v120, v82, v83
	v_max3_f32 v120, v120, v84, v85
	v_max3_f32 v120, v120, v86, v87
	v_max3_f32 v120, v120, v88, v89
	v_max3_f32 v120, v120, v90, v91
	s_nop 0
	v_max3_f32 v120, v120, v92, v93
	v_max3_f32 v120, v120, v94, v95
	ds_bpermute_b32 v121, v113, v120
	s_waitcnt lgkmcnt(0)
	v_max_f32_e32 v121, v121, v121
	v_max_f32_e32 v120, v120, v121
	ds_bpermute_b32 v121, v114, v120
	ds_read_b64_tr_b16 v[186:187], v115 offset:22016
	ds_read_b64_tr_b16 v[184:185], v115 offset:17408
	ds_read_b64_tr_b16 v[188:189], v115 offset:26624
	ds_read_b64_tr_b16 v[190:191], v115 offset:31232
	ds_read_b64_tr_b16 v[192:193], v115 offset:26656
	ds_read_b64_tr_b16 v[194:195], v115 offset:31264
	ds_read_b64_tr_b16 v[196:197], v115 offset:17472
	ds_read_b64_tr_b16 v[198:199], v115 offset:22080
	ds_read_b64_tr_b16 v[200:201], v115 offset:26688
	ds_read_b64_tr_b16 v[202:203], v115 offset:31296
	ds_read_b64_tr_b16 v[204:205], v115 offset:17504
	s_waitcnt lgkmcnt(11)
	v_max3_f32 v120, v119, v120, v121
	ds_read_b64_tr_b16 v[206:207], v115 offset:22112
	v_sub_f32_e32 v80, v80, v120
	v_exp_f32_e32 v80, v80
	v_sub_f32_e32 v81, v81, v120
	v_exp_f32_e32 v81, v81
	v_sub_f32_e32 v82, v82, v120
	v_exp_f32_e32 v82, v82
	v_sub_f32_e32 v83, v83, v120
	v_exp_f32_e32 v83, v83
	v_sub_f32_e32 v84, v84, v120
	v_add_f32_e32 v121, 0, v80
	v_exp_f32_e32 v122, v84
	v_add_f32_e32 v121, v81, v121
	v_add_f32_e32 v121, v82, v121
	v_add_f32_e32 v121, v83, v121
	v_sub_f32_e32 v85, v85, v120
	v_add_f32_e32 v84, v122, v121
	v_exp_f32_e32 v121, v85
	v_sub_f32_e32 v85, v86, v120
	v_exp_f32_e32 v123, v85
	v_sub_f32_e32 v85, v87, v120
	v_exp_f32_e32 v87, v85
	v_sub_f32_e32 v85, v88, v120
	v_exp_f32_e32 v124, v85
	v_sub_f32_e32 v85, v89, v120
	v_add_f32_e32 v84, v121, v84
	v_exp_f32_e32 v125, v85
	v_sub_f32_e32 v85, v90, v120
	v_add_f32_e32 v84, v123, v84
	v_exp_f32_e32 v90, v85
	v_sub_f32_e32 v85, v91, v120
	v_add_f32_e32 v84, v87, v84
	v_exp_f32_e32 v91, v85
	v_sub_f32_e32 v85, v92, v120
	v_add_f32_e32 v84, v124, v84
	v_exp_f32_e32 v92, v85
	v_sub_f32_e32 v85, v93, v120
	v_add_f32_e32 v84, v125, v84
	v_exp_f32_e32 v93, v85
	v_sub_f32_e32 v85, v94, v120
	v_add_f32_e32 v84, v90, v84
	v_exp_f32_e32 v94, v85
	v_sub_f32_e32 v85, v95, v120
	v_add_f32_e32 v84, v91, v84
	v_exp_f32_e32 v95, v85
	v_sub_f32_e32 v119, v119, v120
	v_add_f32_e32 v84, v92, v84
	v_add_f32_e32 v84, v93, v84
	v_exp_f32_e32 v88, v119
	v_add_f32_e32 v84, v94, v84
	v_add_f32_e32 v89, v95, v84
	v_cvt_pk_bf16_f32 v84, v80, v81
	v_cvt_pk_bf16_f32 v85, v82, v83
	v_cvt_pk_bf16_f32 v86, v122, v121
	v_cvt_pk_bf16_f32 v87, v123, v87
	v_cvt_pk_bf16_f32 v81, v90, v91
	v_cvt_pk_bf16_f32 v82, v92, v93
	ds_read_b64_tr_b16 v[122:123], v115 offset:17440
	v_fmac_f32_e32 v89, v118, v88
	v_pk_mul_f32 v[50:51], v[50:51], v[88:89] op_sel_hi:[1,0]
	v_pk_mul_f32 v[48:49], v[48:49], v[88:89] op_sel_hi:[1,0]
	v_cvt_pk_bf16_f32 v80, v124, v125
	v_cvt_pk_bf16_f32 v83, v94, v95
	s_waitcnt lgkmcnt(11)
	v_mfma_f32_16x16x32_bf16 v[48:51], v[184:187], v[84:87], v[48:51]
	ds_read_b64_tr_b16 v[124:125], v115 offset:22048
	v_pk_mul_f32 v[26:27], v[26:27], v[88:89] op_sel_hi:[1,0]
	s_waitcnt lgkmcnt(10)
	v_mfma_f32_16x16x32_bf16 v[48:51], v[188:191], v[80:83], v[48:51]
	ds_read_b64_tr_b16 v[208:209], v115 offset:26720
	ds_read_b64_tr_b16 v[210:211], v115 offset:31328
	v_mul_f32_e64 v24, v24, v88
	v_mul_f32_e64 v25, v25, v88
	v_pk_mul_f32 v[22:23], v[22:23], v[88:89] op_sel_hi:[1,0]
	s_waitcnt lgkmcnt(2)
	v_mfma_f32_16x16x32_bf16 v[24:27], v[122:125], v[84:87], v[24:27]
	ds_read_b64_tr_b16 v[212:213], v115 offset:17536
	ds_read_b64_tr_b16 v[214:215], v115 offset:22144
	ds_read_b64_tr_b16 v[216:217], v115 offset:26752
	ds_read_b64_tr_b16 v[218:219], v115 offset:31360
	ds_read_b64_tr_b16 v[224:225], v115 offset:17568
	ds_read_b64_tr_b16 v[226:227], v115 offset:22176
	ds_read_b64_tr_b16 v[228:229], v115 offset:26784
	ds_read_b64_tr_b16 v[230:231], v115 offset:31392
	ds_read_b64_tr_b16 v[232:233], v115 offset:17600
	ds_read_b64_tr_b16 v[234:235], v115 offset:22208
	v_mul_f32_e64 v20, v20, v88
	v_mul_f32_e64 v21, v21, v88
	v_pk_mul_f32 v[18:19], v[18:19], v[88:89] op_sel_hi:[1,0]
	v_pk_mul_f32 v[16:17], v[16:17], v[88:89] op_sel_hi:[1,0]
	v_mfma_f32_16x16x32_bf16 v[24:27], v[192:195], v[80:83], v[24:27]
	v_pk_mul_f32 v[14:15], v[14:15], v[88:89] op_sel_hi:[1,0]
	v_pk_mul_f32 v[12:13], v[12:13], v[88:89] op_sel_hi:[1,0]
	v_mfma_f32_16x16x32_bf16 v[20:23], v[196:199], v[84:87], v[20:23]
	v_pk_mul_f32 v[10:11], v[10:11], v[88:89] op_sel_hi:[1,0]
	v_pk_mul_f32 v[8:9], v[8:9], v[88:89] op_sel_hi:[1,0]
	v_mfma_f32_16x16x32_bf16 v[20:23], v[200:203], v[80:83], v[20:23]
	v_pk_mul_f32 v[6:7], v[6:7], v[88:89] op_sel_hi:[1,0]
	v_pk_mul_f32 v[4:5], v[4:5], v[88:89] op_sel_hi:[1,0]
	v_mfma_f32_16x16x32_bf16 v[16:19], v[204:207], v[84:87], v[16:19]
	v_pk_mul_f32 v[2:3], v[2:3], v[88:89] op_sel_hi:[1,0]
	v_pk_mul_f32 v[0:1], v[0:1], v[88:89] op_sel_hi:[1,0]
	s_waitcnt lgkmcnt(10)
	v_mfma_f32_16x16x32_bf16 v[16:19], v[208:211], v[80:83], v[16:19]
	ds_read_b64_tr_b16 v[236:237], v115 offset:26816
	ds_read_b64_tr_b16 v[238:239], v115 offset:31424
	v_mov_b32_e32 v119, v120
	v_mov_b32_e32 v118, v89
	s_waitcnt lgkmcnt(10)
	v_mfma_f32_16x16x32_bf16 v[12:15], v[212:215], v[84:87], v[12:15]
	ds_read_b64_tr_b16 v[90:91], v115 offset:17632
	ds_read_b64_tr_b16 v[92:93], v115 offset:22240
	s_waitcnt lgkmcnt(10)
	v_mfma_f32_16x16x32_bf16 v[12:15], v[216:219], v[80:83], v[12:15]
	ds_read_b64_tr_b16 v[240:241], v115 offset:26848
	ds_read_b64_tr_b16 v[242:243], v115 offset:31456
	s_waitcnt lgkmcnt(10)
	v_mfma_f32_16x16x32_bf16 v[8:11], v[224:227], v[84:87], v[8:11]
	s_waitcnt lgkmcnt(8)
	v_mfma_f32_16x16x32_bf16 v[8:11], v[228:231], v[80:83], v[8:11]
	s_waitcnt lgkmcnt(6)
	v_mfma_f32_16x16x32_bf16 v[4:7], v[232:235], v[84:87], v[4:7]
	s_waitcnt lgkmcnt(4)
	v_mfma_f32_16x16x32_bf16 v[4:7], v[236:239], v[80:83], v[4:7]
	s_waitcnt lgkmcnt(2)
	v_mfma_f32_16x16x32_bf16 v[0:3], v[90:93], v[84:87], v[0:3]
	s_waitcnt lgkmcnt(0)
	v_mfma_f32_16x16x32_bf16 v[0:3], v[240:243], v[80:83], v[0:3]

; DI bf16x8 tr2(const bf16_t* p0, const bf16_t* p1) { s16x4 a = trread(p0), b = trread(p1); return __builtin_shufflevector(a, b, 0, 1, 2, 3, 4, 5, 6, 7); }
; DI f32x4 mfma16(bf16x8 a, bf16x8 b, f32x4 c) { return __builtin_amdgcn_mfma_f32_16x16x32_bf16(a, b, c, 0, 0, 0); }
; DI void gdn_scan_item(const P& p, int item, unsigned char* smem) {
;     ...
;             bf16_t* ob = OG + (size_t)prow(b, dir, 64 * c) * 512 + 128 * h + 32 * cq;
;             u32x2 ov; ov.x = pk2(acc[0], acc[1]); ov.y = pk2(acc[2], acc[3]);
;             *(u32x2*)(ob + sgn * ((16 * mt + l15) * 512) + 16 * nt + 4 * g) = ov;
;         }
; #pragma unroll
;         for (int j = 0; j < 2; ++j) {
;             const int dt = 2 * mt + j;
;             st[j] *= dec;
; #pragma unroll
;             for (int k2 = 0; k2 < 2; ++k2) {
;                 const bf16x8 ak = tr2(sKO + (32 * k2 + 8 * g + q4) * 136 + 16 * dt + 4 * p4, sKO + (32 * k2 + 8 * g + 4 + q4) * 136 + 16 * dt + 4 * p4);
;                 st[j] = mfma16(ak, Bv[k2], st[j]);
;             }
;         }
;         sBS[(nt * 4 + mt) * 64 + lane] = __builtin_bit_cast(u32x4, packacc(st[0], st[1]));
.LBB0_500:
	ds_read_b64_tr_b16 v[226:227], v187 offset:35904
	ds_read_b64_tr_b16 v[224:225], v187 offset:34816
	ds_read_b64_tr_b16 v[228:229], v187 offset:34848
	ds_read_b64_tr_b16 v[232:233], v193 offset:34848
	ds_read_b64_tr_b16 v[230:231], v187 offset:35936
	ds_read_b64_tr_b16 v[234:235], v187 offset:44640
	s_ashr_i32 s43, s42, 31
	s_lshl_b64 s[4:5], s[42:43], 10
	s_nop 2
	v_cvt_pk_bf16_f32 v112, v112, v113
	v_cvt_pk_bf16_f32 v113, v114, v115
	v_lshl_add_u64 v[114:115], v[126:127], 0, s[4:5]
	global_store_dwordx2 v[114:115], v[112:113], off
	ds_read_b64_tr_b16 v[114:115], v187 offset:44608
	ds_read_b64_tr_b16 v[112:113], v193 offset:34816
	v_pk_mul_f32 v[98:99], v[98:99], v[132:133] op_sel_hi:[1,0]
	v_pk_mul_f32 v[96:97], v[96:97], v[132:133] op_sel_hi:[1,0]
	v_pk_mul_f32 v[102:103], v[102:103], v[132:133] op_sel_hi:[1,0]
	v_pk_mul_f32 v[100:101], v[100:101], v[132:133] op_sel_hi:[1,0]
	s_waitcnt lgkmcnt(6)
	v_mfma_f32_16x16x32_bf16 v[96:99], v[224:227], v[108:111], v[96:99]
	s_waitcnt lgkmcnt(0)
	v_mfma_f32_16x16x32_bf16 v[96:99], v[112:115], v[104:107], v[96:99]
	s_mov_b64 s[4:5], 0x6000
	v_lshl_add_u64 v[142:143], v[142:143], 0, s[4:5]
	s_mov_b64 s[4:5], 0xc000
	v_mfma_f32_16x16x32_bf16 v[100:103], v[228:231], v[108:111], v[100:103]
	s_add_i32 s21, s21, 12
	s_addk_i32 s22, 0xc0
	s_addk_i32 s24, 0xff40
	v_mfma_f32_16x16x32_bf16 v[100:103], v[232:235], v[104:107], v[100:103]
	v_cvt_pk_bf16_f32 v104, v96, v97
	v_cvt_pk_bf16_f32 v105, v98, v99
	v_lshl_add_u64 v[144:145], v[144:145], 0, s[4:5]
	v_lshl_add_u64 v[146:147], v[146:147], 0, s[4:5]
	v_lshl_add_u64 v[148:149], v[148:149], 0, s[4:5]
	s_nop 2
	v_cvt_pk_bf16_f32 v106, v100, v101
	v_cvt_pk_bf16_f32 v107, v102, v103
	s_cmp_lt_u32 s26, 33
	s_mov_b32 s27, s26
	ds_write_b128 v156, v[104:107]
	s_waitcnt lgkmcnt(0)
	s_cbranch_scc0 .LBB0_640

; DI float lo16(unsigned u) { return __uint_as_float(u << 16); }
; DI float hi16(unsigned u) { return __uint_as_float(u & 0xFFFF0000u); }
; DI bf16x8 tr2(const bf16_t* p0, const bf16_t* p1) { s16x4 a = trread(p0), b = trread(p1); return __builtin_shufflevector(a, b, 0, 1, 2, 3, 4, 5, 6, 7); }
; DI f32x4 mfma16(bf16x8 a, bf16x8 b, f32x4 c) { return __builtin_amdgcn_mfma_f32_16x16x32_bf16(a, b, c, 0, 0, 0); }
; DI void gdn_scan_item(const P& p, int item, unsigned char* smem) {
;     ...
;         const float dec = sdec[c];
;         bf16x8 Bs[4];
; #pragma unroll
;         for (int ks = 0; ks < 4; ++ks) Bs[ks] = __builtin_bit_cast(bf16x8, sBS[(nt * 4 + ks) * 64 + lane]);
;         {
;             f32x4 acc = (f32x4){0.f, 0.f, 0.f, 0.f};
; #pragma unroll
;             for (int ks = 0; ks < 4; ++ks) { const bf16_t* r0 = sW + (16 * mt + l15) * 136 + 32 * ks + 4 * g; acc = mfma16(Bs[ks], ld4x2(r0, r0 + 16), acc); }
;             {
;                 const u32x2 uu = *(const u32x2*)(sU + (16 * mt + l15) * 40 + 16 * nt + 4 * g);
;                 u32x2 vv; vv.x = pk2(lo16(uu.x) - acc[0], hi16(uu.x) - acc[1]); vv.y = pk2(lo16(uu.y) - acc[2], hi16(uu.y) - acc[3]);
;                 *(u32x2*)(sVN + (16 * mt + l15) * 40 + 16 * nt + 4 * g) = vv;
;             }
;         }
;         __syncthreads();
;         bf16x8 Bv[2];
; #pragma unroll
;         for (int k2 = 0; k2 < 2; ++k2) Bv[k2] = tr2(sVN + (32 * k2 + 8 * g + q4) * 40 + 16 * nt + 4 * p4, sVN + (32 * k2 + 8 * g + 4 + q4) * 40 + 16 * nt + 4 * p4);
;         {
;             f32x4 acc = (f32x4){0.f, 0.f, 0.f, 0.f};
; #pragma unroll
;             for (int ks = 0; ks < 4; ++ks) { const bf16_t* r0 = sQI + (16 * mt + l15) * 136 + 32 * ks + 4 * g; acc = mfma16(Bs[ks], ld4x2(r0, r0 + 16), acc); }
; #pragma unroll
;             for (int k2 = 0; k2 < 2; ++k2) acc = mfma16(Bv[k2], ld8(sAT + (16 * mt + l15) * 72 + 32 * k2 + 8 * g), acc);
.LBB0_507:
	ds_read_b128 v[112:115], v117
	ds_read_b128 v[200:203], v117 offset:1024
	ds_read_b128 v[204:207], v117 offset:2048
	ds_read_b128 v[208:211], v117 offset:3072
	v_lshl_add_u32 v134, v121, 1, s28
	v_mov_b32_e32 v104, s21
	ds_read_b32 v132, v104
	v_add_u32_e32 v188, v134, v162
	ds_read2_b64 v[224:227], v188 offset1:4
	ds_read2_b64 v[228:231], v188 offset0:8 offset1:12
	ds_read2_b64 v[232:235], v188 offset0:16 offset1:20
	ds_read2_b64 v[236:239], v188 offset0:24 offset1:28
	v_add_u32_e32 v134, v134, v158
	s_waitcnt lgkmcnt(3)
	v_mfma_f32_16x16x32_bf16 v[104:107], v[112:115], v[224:227], 0
	v_add3_u32 v195, v134, v163, v162
	ds_read_b64 v[240:241], v195 offset:61440
	v_add_u32_e32 v189, 0x4000, v188
	v_add_u32_e32 v134, v134, v159
	s_waitcnt lgkmcnt(3)
	v_mfma_f32_16x16x32_bf16 v[104:107], v[200:203], v[228:231], v[104:107]
	v_lshlrev_b32_e32 v199, 1, v124
	v_add3_u32 v196, v134, v160, v199
	s_waitcnt lgkmcnt(2)
	v_mfma_f32_16x16x32_bf16 v[104:107], v[204:207], v[232:235], v[104:107]
	s_mov_b64 s[42:43], -1
	s_cmp_gt_u32 s26, 3
	s_waitcnt lgkmcnt(1)
	v_mfma_f32_16x16x32_bf16 v[104:107], v[208:211], v[236:239], v[104:107]
	s_waitcnt lgkmcnt(0)
	v_lshlrev_b32_e32 v110, 16, v240
	v_and_b32_e32 v108, 0xffff0000, v240
	s_nop 3
	s_nop 0
	v_sub_f32_e32 v104, v110, v104
	v_sub_f32_e32 v105, v108, v105
	v_cvt_pk_bf16_f32 v104, v104, v105
	v_lshlrev_b32_e32 v105, 16, v241
	v_sub_f32_e32 v105, v105, v106
	v_and_b32_e32 v106, 0xffff0000, v241
	v_sub_f32_e32 v106, v106, v107
	v_cvt_pk_bf16_f32 v105, v105, v106
	ds_write_b64 v123, v[104:105]
	s_waitcnt lgkmcnt(0)
	s_barrier
	ds_read_b64_tr_b16 v[108:109], v164
	ds_read_b64_tr_b16 v[110:111], v165
	ds_read_b64_tr_b16 v[104:105], v183
	ds_read_b64_tr_b16 v[106:107], v184
	ds_read2_b64 v[224:227], v189 offset0:128 offset1:132
	ds_read2_b64 v[228:231], v189 offset0:136 offset1:140
	ds_read2_b64 v[232:235], v189 offset0:144 offset1:148
	ds_read2_b64 v[236:239], v189 offset0:152 offset1:156
	ds_read_b128 v[240:243], v196 offset:52224
	ds_read_b128 v[244:247], v196 offset:52288
	s_waitcnt lgkmcnt(5)
	v_mfma_f32_16x16x32_bf16 v[112:115], v[112:115], v[224:227], 0
	s_waitcnt lgkmcnt(4)
	v_mfma_f32_16x16x32_bf16 v[112:115], v[200:203], v[228:231], v[112:115]
	s_waitcnt lgkmcnt(3)
	v_mfma_f32_16x16x32_bf16 v[112:115], v[204:207], v[232:235], v[112:115]
	s_waitcnt lgkmcnt(2)
	v_mfma_f32_16x16x32_bf16 v[112:115], v[208:211], v[236:239], v[112:115]
	s_waitcnt lgkmcnt(1)
	v_mfma_f32_16x16x32_bf16 v[112:115], v[108:111], v[240:243], v[112:115]
	s_waitcnt lgkmcnt(0)
	v_mfma_f32_16x16x32_bf16 v[112:115], v[104:107], v[244:247], v[112:115]
	s_cbranch_scc0 .LBB0_509
	s_add_i32 s6, s22, 0xfffffe80
	s_add_i32 s7, s24, 0x80
	s_and_b64 s[4:5], s[38:39], exec
	s_cselect_b32 s4, s6, s7
	s_add_i32 s40, s4, s2
	s_mov_b64 s[42:43], 0

; DI bf16x8 tr2(const bf16_t* p0, const bf16_t* p1) { s16x4 a = trread(p0), b = trread(p1); return __builtin_shufflevector(a, b, 0, 1, 2, 3, 4, 5, 6, 7); }
; DI f32x4 mfma16(bf16x8 a, bf16x8 b, f32x4 c) { return __builtin_amdgcn_mfma_f32_16x16x32_bf16(a, b, c, 0, 0, 0); }
; DI void gdn_scan_item(const P& p, int item, unsigned char* smem) {
;     ...
;         bf16_t* sW = (bf16_t*)(smem + buf * BUFB); bf16_t* sQI = sW + 64 * 136; bf16_t* sKO = sQI + 64 * 136; bf16_t* sAT = sKO + 64 * 136; bf16_t* sU = sAT + 64 * 72;
; #pragma unroll
;         for (int k = 0; k < 2; ++k) {
;             const int e = tid + 512 * k, r = e >> 4, ch = e & 15; const int off = r * 136 + 8 * ch;
;             *(u32x4*)(sW + off) = rr[k]; *(u32x4*)(sQI + off) = rr[2 + k]; *(u32x4*)(sKO + off) = rr[4 + k];
;         }
;         { const int r = tid >> 3, ch = tid & 7; *(u32x4*)(sAT + r * 72 + 8 * ch) = rr[6]; }
;         if (tid < 256) { const int r = tid >> 2, ch = tid & 3; *(u32x4*)(sU + r * 40 + 8 * ch) = rr[7]; }
;     ...
; #pragma unroll
;         for (int j = 0; j < 2; ++j) {
;             const int dt = 2 * mt + j;
;             st[j] *= dec;
; #pragma unroll
;             for (int k2 = 0; k2 < 2; ++k2) {
;                 const bf16x8 ak = tr2(sKO + (32 * k2 + 8 * g + q4) * 136 + 16 * dt + 4 * p4, sKO + (32 * k2 + 8 * g + 4 + q4) * 136 + 16 * dt + 4 * p4);
;                 st[j] = mfma16(ak, Bv[k2], st[j]);
;             }
;         }
;         sBS[(nt * 4 + mt) * 64 + lane] = __builtin_bit_cast(u32x4, packacc(st[0], st[1]));
.LBB0_511:
	v_lshl_add_u32 v134, v125, 1, s28
	v_lshlrev_b32_e32 v197, 1, v157
	v_add3_u32 v187, v134, v185, v197
	ds_read_b64_tr_b16 v[226:227], v187 offset:35904
	ds_read_b64_tr_b16 v[224:225], v187 offset:34816
	ds_read_b64_tr_b16 v[230:231], v187 offset:44608
	ds_read_b64_tr_b16 v[234:235], v187 offset:35936
	ds_read_b64_tr_b16 v[232:233], v187 offset:34848
	ds_read_b64_tr_b16 v[238:239], v187 offset:44640
	v_add3_u32 v193, v134, v186, v197
	ds_read_b64_tr_b16 v[228:229], v193 offset:34816
	ds_read_b64_tr_b16 v[236:237], v193 offset:34848
	v_pk_mul_f32 v[98:99], v[98:99], v[132:133] op_sel_hi:[1,0]
	v_pk_mul_f32 v[96:97], v[96:97], v[132:133] op_sel_hi:[1,0]
	v_pk_mul_f32 v[102:103], v[102:103], v[132:133] op_sel_hi:[1,0]
	v_pk_mul_f32 v[100:101], v[100:101], v[132:133] op_sel_hi:[1,0]
	s_waitcnt lgkmcnt(6)
	v_mfma_f32_16x16x32_bf16 v[96:99], v[224:227], v[108:111], v[96:99]
	s_ashr_i32 s41, s40, 31
	s_lshl_b64 s[4:5], s[40:41], 10
	s_waitcnt lgkmcnt(3)
	v_mfma_f32_16x16x32_bf16 v[100:103], v[232:235], v[108:111], v[100:103]
	s_bitcmp1_b32 s27, 0
	v_lshl_add_u64 v[108:109], v[126:127], 0, s[4:5]
	s_cselect_b32 s4, 0x10400, 0
	s_waitcnt lgkmcnt(1)
	v_mfma_f32_16x16x32_bf16 v[96:99], v[228:231], v[104:107], v[96:99]
	s_add_i32 s27, s57, s4
	v_cvt_pk_bf16_f32 v112, v112, v113
	v_cvt_pk_bf16_f32 v113, v114, v115
	s_waitcnt lgkmcnt(0)
	v_mfma_f32_16x16x32_bf16 v[100:103], v[236:239], v[104:107], v[100:103]
	global_store_dwordx2 v[108:109], v[112:113], off
	s_nop 1
	v_cvt_pk_bf16_f32 v104, v96, v97
	v_cvt_pk_bf16_f32 v105, v98, v99
	s_nop 2
	v_cvt_pk_bf16_f32 v106, v100, v101
	v_cvt_pk_bf16_f32 v107, v102, v103
	ds_write_b128 v156, v[104:107]
	v_lshl_add_u32 v104, v120, 1, s27
	s_waitcnt vmcnt(14)
	ds_write_b128 v104, v[28:31]
	s_waitcnt vmcnt(13)
	ds_write_b128 v104, v[32:35] offset:17408
	s_waitcnt vmcnt(12)
	ds_write_b128 v104, v[40:43] offset:34816
	v_lshl_add_u32 v104, v122, 1, s27
	s_waitcnt vmcnt(11)
	ds_write_b128 v104, v[48:51]
	s_waitcnt vmcnt(10)
	ds_write_b128 v104, v[52:55] offset:17408
	s_waitcnt vmcnt(9)
	ds_write_b128 v104, v[64:67] offset:34816
	v_add3_u32 v104, s27, v119, v116
	s_waitcnt vmcnt(3)
	ds_write_b128 v104, v[72:75] offset:52224
	s_waitcnt lgkmcnt(0)
	s_and_saveexec_b64 s[40:41], s[0:1]
	v_add3_u32 v104, s27, v161, v198
	ds_write_b128 v104, v[44:47] offset:61440
	s_or_b64 exec, exec, s[40:41]
	s_cmp_gt_u32 s26, 31
	v_readlane_b32 s12, v254, 56
	s_waitcnt lgkmcnt(0)
	s_barrier
	v_readlane_b32 s13, v254, 57
	s_cbranch_scc1 .LBB0_517
	v_add_co_u32_e32 v28, vcc, 0x13f5c000, v154
	s_nop 1
	v_addc_co_u32_e32 v29, vcc, 0, v155, vcc
	v_add_co_u32_e32 v32, vcc, 0x1515c000, v154
	s_nop 1
	v_addc_co_u32_e32 v33, vcc, 0, v155, vcc
	v_add_co_u32_e32 v40, vcc, 0x1635c000, v154
	global_load_dwordx4 v[28:31], v[28:29], off
	s_nop 0
	global_load_dwordx4 v[32:35], v[32:33], off
	v_addc_co_u32_e32 v41, vcc, 0, v155, vcc
	v_add_co_u32_e32 v48, vcc, 0x13f5c000, v152
	global_load_dwordx4 v[40:43], v[40:41], off
	s_nop 0
	v_addc_co_u32_e32 v49, vcc, 0, v153, vcc
	v_add_co_u32_e32 v52, vcc, 0x1515c000, v152
	s_nop 1
	v_addc_co_u32_e32 v53, vcc, 0, v153, vcc
	v_add_co_u32_e32 v64, vcc, 0x1635c000, v152
	global_load_dwordx4 v[48:51], v[48:49], off
	s_nop 0
	global_load_dwordx4 v[52:55], v[52:53], off
	v_addc_co_u32_e32 v65, vcc, 0, v153, vcc
	v_add_co_u32_e32 v72, vcc, 0x17554000, v150
	global_load_dwordx4 v[64:67], v[64:65], off
	s_nop 0
	v_addc_co_u32_e32 v73, vcc, 0, v151, vcc
	global_load_dwordx4 v[72:75], v[72:73], off
	s_and_saveexec_b64 s[40:41], s[0:1]
	s_cbranch_execz .LBB0_516
	v_lshl_add_u64 v[44:45], v[144:145], 0, s[44:45]
	v_add_co_u32_e32 v44, vcc, 0x12d5c000, v44
	s_nop 1
	v_addc_co_u32_e32 v45, vcc, 0, v45, vcc
	global_load_dwordx4 v[44:47], v[44:45], off nt

; DI void gdn_scan_item(const P& p, int item, unsigned char* smem) {
;     ...
;         storel(R, c & 1);
;         __syncthreads();
;         loadr(R, c + 3);
;         const bf16_t* sW = (const bf16_t*)(smem + (c & 1) * BUFB); const bf16_t* sQI = sW + 64 * 136; const bf16_t* sKO = sQI + 64 * 136; const bf16_t* sAT = sKO + 64 * 136; const bf16_t* sU = sAT + 64 * 72;
;         const float dec = sdec[c];
;         bf16x8 Bs[4];
; #pragma unroll
;         for (int ks = 0; ks < 4; ++ks) Bs[ks] = __builtin_bit_cast(bf16x8, sBS[(nt * 4 + ks) * 64 + lane]);
;         {
;             f32x4 acc = (f32x4){0.f, 0.f, 0.f, 0.f};
; #pragma unroll
;             for (int ks = 0; ks < 4; ++ks) { const bf16_t* r0 = sW + (16 * mt + l15) * 136 + 32 * ks + 4 * g; acc = mfma16(Bs[ks], ld4x2(r0, r0 + 16), acc); }
;             {
;                 const u32x2 uu = *(const u32x2*)(sU + (16 * mt + l15) * 40 + 16 * nt + 4 * g);
;                 u32x2 vv; vv.x = pk2(lo16(uu.x) - acc[0], hi16(uu.x) - acc[1]); vv.y = pk2(lo16(uu.y) - acc[2], hi16(uu.y) - acc[3]);
;                 *(u32x2*)(sVN + (16 * mt + l15) * 40 + 16 * nt + 4 * g) = vv;
;             }
;         }
;         __syncthreads();
;         bf16x8 Bv[2];
; #pragma unroll
;         for (int k2 = 0; k2 < 2; ++k2) Bv[k2] = tr2(sVN + (32 * k2 + 8 * g + q4) * 40 + 16 * nt + 4 * p4, sVN + (32 * k2 + 8 * g + 4 + q4) * 40 + 16 * nt + 4 * p4);
;         {
;             f32x4 acc = (f32x4){0.f, 0.f, 0.f, 0.f};
; #pragma unroll
;             for (int ks = 0; ks < 4; ++ks) { const bf16_t* r0 = sQI + (16 * mt + l15) * 136 + 32 * ks + 4 * g; acc = mfma16(Bs[ks], ld4x2(r0, r0 + 16), acc); }
; #pragma unroll
;             for (int k2 = 0; k2 < 2; ++k2) acc = mfma16(Bv[k2], ld8(sAT + (16 * mt + l15) * 72 + 32 * k2 + 8 * g), acc);
;             bf16_t* ob = OG + (size_t)prow(b, dir, 64 * c) * 512 + 128 * h + 32 * cq;
;             u32x2 ov; ov.x = pk2(acc[0], acc[1]); ov.y = pk2(acc[2], acc[3]);
;             *(u32x2*)(ob + sgn * ((16 * mt + l15) * 512) + 16 * nt + 4 * g) = ov;
;         }
; #pragma unroll
;         for (int j = 0; j < 2; ++j) {
;             const int dt = 2 * mt + j;
;             st[j] *= dec;
; #pragma unroll
;             for (int k2 = 0; k2 < 2; ++k2) {
;                 const bf16x8 ak = tr2(sKO + (32 * k2 + 8 * g + q4) * 136 + 16 * dt + 4 * p4, sKO + (32 * k2 + 8 * g + 4 + q4) * 136 + 16 * dt + 4 * p4);
.LBB0_517:
	ds_read_b128 v[110:113], v117
	ds_read_b128 v[200:203], v117 offset:1024
	ds_read_b128 v[204:207], v117 offset:2048
	ds_read_b128 v[208:211], v117 offset:3072
	v_lshl_add_u32 v109, v121, 1, s27
	v_mov_b32_e32 v104, s21
	ds_read_b32 v108, v104 offset:4
	v_add_u32_e32 v132, v109, v162
	ds_read2_b64 v[224:227], v132 offset1:4
	ds_read2_b64 v[228:231], v132 offset0:8 offset1:12
	ds_read2_b64 v[236:239], v132 offset0:16 offset1:20
	ds_read2_b64 v[240:243], v132 offset0:24 offset1:28
	v_add_u32_e32 v109, v109, v158
	s_waitcnt lgkmcnt(3)
	v_mfma_f32_16x16x32_bf16 v[104:107], v[110:113], v[224:227], 0
	v_add3_u32 v114, v109, v163, v162
	ds_read_b64 v[232:233], v114 offset:61440
	v_add_u32_e32 v109, v109, v159
	s_waitcnt lgkmcnt(3)
	v_mfma_f32_16x16x32_bf16 v[104:107], v[200:203], v[228:231], v[104:107]
	v_add3_u32 v109, v109, v160, v199
	s_waitcnt lgkmcnt(0)
	v_lshlrev_b32_e32 v134, 16, v232
	v_mfma_f32_16x16x32_bf16 v[104:107], v[204:207], v[236:239], v[104:107]
	v_and_b32_e32 v114, 0xffff0000, v232
	s_sub_i32 s4, s22, 64
	v_mfma_f32_16x16x32_bf16 v[104:107], v[208:211], v[240:243], v[104:107]
	s_add_i32 s5, s22, 0xfffffec0
	s_cmp_lt_u32 s26, 3
	s_movk_i32 s6, 0x8ff
	s_nop 4
	v_sub_f32_e32 v104, v134, v104
	v_sub_f32_e32 v105, v114, v105
	v_cvt_pk_bf16_f32 v104, v104, v105
	v_lshlrev_b32_e32 v105, 16, v233
	v_sub_f32_e32 v105, v105, v106
	v_and_b32_e32 v106, 0xffff0000, v233
	v_sub_f32_e32 v106, v106, v107
	v_cvt_pk_bf16_f32 v105, v105, v106
	v_add_u32_e32 v114, 0x4000, v132
	ds_write_b64 v123, v[104:105]
	s_waitcnt lgkmcnt(0)
	s_barrier
	ds_read_b64_tr_b16 v[224:225], v164
	ds_read_b64_tr_b16 v[226:227], v165
	ds_read_b64_tr_b16 v[228:229], v183
	ds_read_b64_tr_b16 v[230:231], v184
	ds_read2_b64 v[232:235], v114 offset0:128 offset1:132
	ds_read2_b64 v[236:239], v114 offset0:136 offset1:140
	ds_read2_b64 v[240:243], v114 offset0:144 offset1:148
	ds_read2_b64 v[244:247], v114 offset0:152 offset1:156
	ds_read_b128 v[248:251], v109 offset:52224
	s_waitcnt lgkmcnt(4)
	v_mfma_f32_16x16x32_bf16 v[110:113], v[110:113], v[232:235], 0
	ds_read_b128 v[232:235], v109 offset:52288
	s_cselect_b32 s6, 0xff, s6
	s_cselect_b32 s7, s4, s5
	s_waitcnt lgkmcnt(4)
	v_mfma_f32_16x16x32_bf16 v[110:113], v[200:203], v[236:239], v[110:113]
	s_cselect_b32 s8, s3, s2
	s_add_i32 s4, s6, s24
	s_waitcnt lgkmcnt(3)
	v_mfma_f32_16x16x32_bf16 v[110:113], v[204:207], v[240:243], v[110:113]
	s_add_i32 s6, s4, 0xfffff741
	s_and_b64 s[4:5], s[38:39], exec
	s_waitcnt lgkmcnt(2)
	v_mfma_f32_16x16x32_bf16 v[110:113], v[208:211], v[244:247], v[110:113]
	s_cselect_b32 s4, s7, s6
	s_add_i32 s4, s4, s8
	s_waitcnt lgkmcnt(1)
	v_mfma_f32_16x16x32_bf16 v[110:113], v[224:227], v[248:251], v[110:113]
	s_ashr_i32 s5, s4, 31
	s_lshl_b64 s[4:5], s[4:5], 10
	s_waitcnt lgkmcnt(0)
	v_mfma_f32_16x16x32_bf16 v[110:113], v[228:231], v[232:235], v[110:113]
	v_mul_f32_e64 v98, v98, v108
	v_mul_f32_e64 v99, v99, v108
	v_pk_mul_f32 v[96:97], v[96:97], v[108:109] op_sel_hi:[1,0]
	v_lshl_add_u32 v109, v125, 1, s27
	s_nop 3
	v_cvt_pk_bf16_f32 v110, v110, v111
	v_cvt_pk_bf16_f32 v111, v112, v113
	v_lshl_add_u64 v[112:113], v[126:127], 0, s[4:5]
	global_store_dwordx2 v[112:113], v[110:111], off
	v_add3_u32 v114, v109, v185, v197
	ds_read_b64_tr_b16 v[238:239], v114 offset:35904
	ds_read_b64_tr_b16 v[236:237], v114 offset:34816
	ds_read_b64_tr_b16 v[240:241], v114 offset:34848
	ds_read_b64_tr_b16 v[246:247], v114 offset:44608
	ds_read_b64_tr_b16 v[242:243], v114 offset:35936
	ds_read_b64_tr_b16 v[250:251], v114 offset:44640
	s_waitcnt lgkmcnt(4)
	v_mfma_f32_16x16x32_bf16 v[96:99], v[236:239], v[224:227], v[96:99]
	v_add3_u32 v109, v109, v186, v197
	ds_read_b64_tr_b16 v[244:245], v109 offset:34816
	ds_read_b64_tr_b16 v[248:249], v109 offset:34848
	v_pk_mul_f32 v[102:103], v[102:103], v[108:109] op_sel_hi:[1,0]
	v_pk_mul_f32 v[100:101], v[100:101], v[108:109] op_sel_hi:[1,0]
	s_waitcnt lgkmcnt(1)
	v_mfma_f32_16x16x32_bf16 v[96:99], v[244:247], v[228:231], v[96:99]
	v_mfma_f32_16x16x32_bf16 v[100:103], v[240:243], v[224:227], v[100:103]
	s_waitcnt lgkmcnt(0)
	v_mfma_f32_16x16x32_bf16 v[100:103], v[248:251], v[228:231], v[100:103]
	s_nop 3
	s_nop 0
	v_cvt_pk_bf16_f32 v104, v96, v97
	v_cvt_pk_bf16_f32 v105, v98, v99
	s_nop 1
	v_cvt_pk_bf16_f32 v106, v100, v101
	v_cvt_pk_bf16_f32 v107, v102, v103
	ds_write_b128 v156, v[104:107]
	s_waitcnt vmcnt(8)
	ds_write_b128 v190, v[56:59]
	s_waitcnt vmcnt(7)
	ds_write_b128 v190, v[60:63] offset:17408
	s_waitcnt vmcnt(6)
	ds_write_b128 v190, v[68:71] offset:34816
	s_waitcnt vmcnt(5)
	ds_write_b128 v192, v[76:79]
	s_waitcnt vmcnt(4)
	ds_write_b128 v192, v[80:83] offset:17408
	s_waitcnt vmcnt(3)
	ds_write_b128 v192, v[84:87] offset:34816
	s_waitcnt vmcnt(2)
	ds_write_b128 v194, v[92:95] offset:52224
	s_waitcnt lgkmcnt(0)
	s_and_saveexec_b64 s[40:41], s[0:1]
	ds_write_b128 v191, v[88:91] offset:61440
	s_or_b64 exec, exec, s[40:41]
	s_cmp_gt_u32 s26, 30
	s_waitcnt lgkmcnt(0)
	s_barrier
	s_cbranch_scc1 .LBB0_523
	v_add_co_u32_e32 v56, vcc, 0x13f60000, v154
	s_nop 1
	v_addc_co_u32_e32 v57, vcc, 0, v155, vcc
	v_add_co_u32_e32 v60, vcc, 0x15160000, v154
	s_nop 1
	v_addc_co_u32_e32 v61, vcc, 0, v155, vcc
	v_add_co_u32_e32 v68, vcc, 0x16360000, v154
	global_load_dwordx4 v[56:59], v[56:57], off
	s_nop 0
	global_load_dwordx4 v[60:63], v[60:61], off
	v_addc_co_u32_e32 v69, vcc, 0, v155, vcc
	v_add_co_u32_e32 v76, vcc, 0x13f60000, v152
	global_load_dwordx4 v[68:71], v[68:69], off
	s_nop 0
	v_addc_co_u32_e32 v77, vcc, 0, v153, vcc
	v_add_co_u32_e32 v80, vcc, 0x15160000, v152
	s_nop 1
	v_addc_co_u32_e32 v81, vcc, 0, v153, vcc
	v_add_co_u32_e32 v84, vcc, 0x16360000, v152
	global_load_dwordx4 v[76:79], v[76:77], off
	s_nop 0
	global_load_dwordx4 v[80:83], v[80:81], off
	v_addc_co_u32_e32 v85, vcc, 0, v153, vcc
	v_add_co_u32_e32 v92, vcc, 0x17556000, v150
	global_load_dwordx4 v[84:87], v[84:85], off
	s_nop 0
	v_addc_co_u32_e32 v93, vcc, 0, v151, vcc
	global_load_dwordx4 v[92:95], v[92:93], off
	s_and_saveexec_b64 s[40:41], s[0:1]
	s_cbranch_execz .LBB0_522
	v_lshl_add_u64 v[88:89], v[144:145], 0, s[44:45]
	v_add_co_u32_e32 v88, vcc, 0x12d60000, v88
	s_nop 1
	v_addc_co_u32_e32 v89, vcc, 0, v89, vcc
	global_load_dwordx4 v[88:91], v[88:89], off nt

; DI float lo16(unsigned u) { return __uint_as_float(u << 16); }
; DI float hi16(unsigned u) { return __uint_as_float(u & 0xFFFF0000u); }
; DI bf16x8 tr2(const bf16_t* p0, const bf16_t* p1) { s16x4 a = trread(p0), b = trread(p1); return __builtin_shufflevector(a, b, 0, 1, 2, 3, 4, 5, 6, 7); }
; DI f32x4 mfma16(bf16x8 a, bf16x8 b, f32x4 c) { return __builtin_amdgcn_mfma_f32_16x16x32_bf16(a, b, c, 0, 0, 0); }
; DI void gdn_scan_item(const P& p, int item, unsigned char* smem) {
;     ...
;         const float dec = sdec[c];
;         bf16x8 Bs[4];
; #pragma unroll
;         for (int ks = 0; ks < 4; ++ks) Bs[ks] = __builtin_bit_cast(bf16x8, sBS[(nt * 4 + ks) * 64 + lane]);
;         {
;             f32x4 acc = (f32x4){0.f, 0.f, 0.f, 0.f};
; #pragma unroll
;             for (int ks = 0; ks < 4; ++ks) { const bf16_t* r0 = sW + (16 * mt + l15) * 136 + 32 * ks + 4 * g; acc = mfma16(Bs[ks], ld4x2(r0, r0 + 16), acc); }
;             {
;                 const u32x2 uu = *(const u32x2*)(sU + (16 * mt + l15) * 40 + 16 * nt + 4 * g);
;                 u32x2 vv; vv.x = pk2(lo16(uu.x) - acc[0], hi16(uu.x) - acc[1]); vv.y = pk2(lo16(uu.y) - acc[2], hi16(uu.y) - acc[3]);
;                 *(u32x2*)(sVN + (16 * mt + l15) * 40 + 16 * nt + 4 * g) = vv;
;             }
;         }
;         __syncthreads();
;         bf16x8 Bv[2];
; #pragma unroll
;         for (int k2 = 0; k2 < 2; ++k2) Bv[k2] = tr2(sVN + (32 * k2 + 8 * g + q4) * 40 + 16 * nt + 4 * p4, sVN + (32 * k2 + 8 * g + 4 + q4) * 40 + 16 * nt + 4 * p4);
;         {
;             f32x4 acc = (f32x4){0.f, 0.f, 0.f, 0.f};
; #pragma unroll
;             for (int ks = 0; ks < 4; ++ks) { const bf16_t* r0 = sQI + (16 * mt + l15) * 136 + 32 * ks + 4 * g; acc = mfma16(Bs[ks], ld4x2(r0, r0 + 16), acc); }
; #pragma unroll
;             for (int k2 = 0; k2 < 2; ++k2) acc = mfma16(Bv[k2], ld8(sAT + (16 * mt + l15) * 72 + 32 * k2 + 8 * g), acc);
.LBB0_523:
	ds_read_b128 v[112:115], v117
	ds_read_b128 v[150:153], v117 offset:1024
	ds_read_b128 v[198:201], v117 offset:2048
	ds_read_b128 v[202:205], v117 offset:3072
	ds_read2_b64 v[224:227], v188 offset1:4
	ds_read2_b64 v[228:231], v188 offset0:8 offset1:12
	ds_read2_b64 v[232:235], v188 offset0:16 offset1:20
	ds_read2_b64 v[236:239], v188 offset0:24 offset1:28
	ds_read_b64 v[240:241], v195 offset:61440
	v_mov_b32_e32 v104, s21
	ds_read_b32 v132, v104 offset:8
	s_mov_b64 s[40:41], -1
	s_cmp_gt_u32 s26, 1
	s_waitcnt lgkmcnt(5)
	v_mfma_f32_16x16x32_bf16 v[104:107], v[112:115], v[224:227], 0
	s_waitcnt lgkmcnt(4)
	v_mfma_f32_16x16x32_bf16 v[104:107], v[150:153], v[228:231], v[104:107]
	s_waitcnt lgkmcnt(3)
	v_mfma_f32_16x16x32_bf16 v[104:107], v[198:201], v[232:235], v[104:107]
	s_waitcnt lgkmcnt(2)
	v_mfma_f32_16x16x32_bf16 v[104:107], v[202:205], v[236:239], v[104:107]
	s_waitcnt lgkmcnt(1)
	v_lshlrev_b32_e32 v110, 16, v240
	v_and_b32_e32 v108, 0xffff0000, v240
	s_nop 3
	s_nop 0
	v_sub_f32_e32 v104, v110, v104
	v_sub_f32_e32 v105, v108, v105
	v_cvt_pk_bf16_f32 v104, v104, v105
	v_lshlrev_b32_e32 v105, 16, v241
	v_sub_f32_e32 v105, v105, v106
	v_and_b32_e32 v106, 0xffff0000, v241
	v_sub_f32_e32 v106, v106, v107
	v_cvt_pk_bf16_f32 v105, v105, v106
	ds_write_b64 v123, v[104:105]
	s_waitcnt lgkmcnt(0)
	s_barrier
	ds_read_b64_tr_b16 v[108:109], v164
	ds_read_b64_tr_b16 v[110:111], v165
	ds_read_b64_tr_b16 v[104:105], v183
	ds_read_b64_tr_b16 v[106:107], v184
	ds_read2_b64 v[224:227], v189 offset0:128 offset1:132
	ds_read2_b64 v[228:231], v189 offset0:136 offset1:140
	ds_read2_b64 v[232:235], v189 offset0:144 offset1:148
	ds_read2_b64 v[236:239], v189 offset0:152 offset1:156
	ds_read_b128 v[240:243], v196 offset:52224
	ds_read_b128 v[244:247], v196 offset:52288
	s_waitcnt lgkmcnt(5)
	v_mfma_f32_16x16x32_bf16 v[112:115], v[112:115], v[224:227], 0
	s_waitcnt lgkmcnt(4)
	v_mfma_f32_16x16x32_bf16 v[112:115], v[150:153], v[228:231], v[112:115]
	s_waitcnt lgkmcnt(3)
	v_mfma_f32_16x16x32_bf16 v[112:115], v[198:201], v[232:235], v[112:115]
	s_waitcnt lgkmcnt(2)
	v_mfma_f32_16x16x32_bf16 v[112:115], v[202:205], v[236:239], v[112:115]
	s_waitcnt lgkmcnt(1)
	v_mfma_f32_16x16x32_bf16 v[112:115], v[108:111], v[240:243], v[112:115]
	s_waitcnt lgkmcnt(0)
	v_mfma_f32_16x16x32_bf16 v[112:115], v[104:107], v[244:247], v[112:115]
	s_cbranch_scc0 .LBB0_525
	s_add_i32 s6, s22, 0xffffff00
	s_and_b64 s[4:5], s[38:39], exec
	s_cselect_b32 s4, s6, s24
	s_add_i32 s42, s4, s2
	s_mov_b64 s[40:41], 0

; DI bf16x8 tr2(const bf16_t* p0, const bf16_t* p1) { s16x4 a = trread(p0), b = trread(p1); return __builtin_shufflevector(a, b, 0, 1, 2, 3, 4, 5, 6, 7); }
; DI f32x4 mfma16(bf16x8 a, bf16x8 b, f32x4 c) { return __builtin_amdgcn_mfma_f32_16x16x32_bf16(a, b, c, 0, 0, 0); }
; DI void gla_scan_item(const P& p, int seq, unsigned char* smem) {
;     ...
;     auto compute = [&](int c) {
;         const unsigned char* base = smem + (c & 1) * BUFB;
;         const bf16_t* sat = (const bf16_t*)base; const bf16_t* sqt = (const bf16_t*)(base + 2560); const bf16_t* sko = (const bf16_t*)(base + 2560 + 4608); const bf16_t* sv = (const bf16_t*)(base + 2560 + 9216); const float* sdc = (const float*)(base + 2560 + 9216 + 8704);
;         const int dv0 = 16 * w;
;         const bf16x8 vb = tr2(sv + (8 * g + q4) * 136 + dv0 + 4 * p4, sv + (8 * g + 4 + q4) * 136 + dv0 + 4 * p4);
;         bf16x8 bs[2];
;         bs[0] = packacc(st[0], st[1]); bs[1] = packacc(st[2], st[3]);
; #pragma unroll
;         for (int mt = 0; mt < 2; ++mt) {
;             f32x4 acc = (f32x4){0.f, 0.f, 0.f, 0.f};
;             acc = mfma16(vb, ld8(sat + (16 * mt + l15) * 40 + 8 * g), acc);
; #pragma unroll
;             for (int ks = 0; ks < 2; ++ks) {
;                 const bf16_t* r0 = sqt + (16 * mt + l15) * 72 + 32 * ks + 4 * g;
;                 acc = mfma16(bs[ks], ld4x2(r0, r0 + 16), acc);
;             }
;             bf16_t* ob = OG + (size_t)prow(b, dir, 32 * c) * 512 + 128 * h;
;             u32x2 ov; ov.x = pk2(acc[0], acc[1]); ov.y = pk2(acc[2], acc[3]);
;             *(u32x2*)(ob + sgn * ((16 * mt + l15) * 512) + dv0 + 4 * g) = ov;
;         }
; #pragma unroll
;         for (int dt = 0; dt < 4; ++dt) {
;             const bf16x8 ak = tr2(sko + (8 * g + q4) * 72 + 16 * dt + 4 * p4, sko + (8 * g + 4 + q4) * 72 + 16 * dt + 4 * p4);
; #pragma unroll
;             for (int r = 0; r < 4; ++r) st[dt][r] *= sdc[16 * dt + 4 * g + r];
;             st[dt] = mfma16(ak, vb, st[dt]);
;         }
.LBB0_579:
	ds_read_b64_tr_b16 v[200:201], v123 offset:32512
	ds_read_b64_tr_b16 v[202:203], v124 offset:32512
	ds_read_b128 v[204:207], v125 offset:20736
	ds_read2_b64 v[208:211], v159 offset0:96 offset1:100
	ds_read2_b64 v[212:215], v159 offset0:104 offset1:108
	ds_read2_b64 v[216:219], v162 offset0:96 offset1:100
	ds_read_b128 v[224:227], v127 offset:20736
	ds_read2_b64 v[228:231], v162 offset0:104 offset1:108
	ds_read2_b32 v[232:233], v163 offset1:1
	ds_read2_b32 v[234:235], v183 offset1:1
	ds_read_b64_tr_b16 v[238:239], v147 offset:27904
	ds_read_b64_tr_b16 v[242:243], v147 offset:27936
	v_cvt_pk_bf16_f32 v84, v92, s0
	v_cvt_pk_bf16_f32 v87, v93, s0
	v_cvt_pk_bf16_f32 v85, v94, s0
	v_cvt_pk_bf16_f32 v112, v95, s0
	v_cvt_pk_bf16_f32 v86, v72, s0
	v_cvt_pk_bf16_f32 v113, v73, s0
	v_cvt_pk_bf16_f32 v134, v74, s0
	v_cvt_pk_bf16_f32 v135, v75, s0
	v_perm_b32 v86, v113, v86, s25
	v_perm_b32 v85, v112, v85, s25
	v_perm_b32 v84, v87, v84, s25
	v_perm_b32 v87, v135, v134, s25
	s_waitcnt lgkmcnt(9)
	v_mfma_f32_16x16x32_bf16 v[76:79], v[200:203], v[204:207], 0
	ds_read_b64_tr_b16 v[236:237], v146 offset:27904
	ds_read_b64_tr_b16 v[240:241], v146 offset:27936
	ds_read2_b32 v[244:245], v185 offset1:1
	s_add_i32 s4, s26, 0x60
	s_add_i32 s5, s26, 0xffffff60
	s_add_i32 s6, s27, 0xfffff800
	v_cvt_pk_bf16_f32 v154, v80, s0
	v_cvt_pk_bf16_f32 v155, v81, s0
	v_cvt_pk_bf16_f32 v156, v82, s0
	v_cvt_pk_bf16_f32 v157, v83, s0
	v_cvt_pk_bf16_f32 v158, v88, s0
	v_cvt_pk_bf16_f32 v160, v89, s0
	v_cvt_pk_bf16_f32 v161, v90, s0
	v_cvt_pk_bf16_f32 v188, v91, s0
	s_and_b64 s[2:3], s[0:1], exec
	s_cselect_b32 s2, s4, s6
	s_waitcnt lgkmcnt(11)
	v_mfma_f32_16x16x32_bf16 v[76:79], v[84:87], v[208:211], v[76:79]
	ds_read2_b32 v[246:247], v184 offset1:1
	v_perm_b32 v152, v160, v158, s25
	v_perm_b32 v151, v157, v156, s25
	v_perm_b32 v150, v155, v154, s25
	v_perm_b32 v153, v188, v161, s25
	s_add_i32 s4, s2, s22
	s_and_b64 s[2:3], s[0:1], exec
	s_cselect_b32 s2, s5, s27
	s_add_i32 s2, s2, s21
	s_cmp_lt_u32 s24, 3
	s_waitcnt lgkmcnt(11)
	v_mfma_f32_16x16x32_bf16 v[76:79], v[150:153], v[212:215], v[76:79]
	ds_read_b64_tr_b16 v[248:249], v146 offset:27968
	s_cselect_b32 s2, s4, s2
	s_ashr_i32 s3, s2, 31
	s_lshl_b64 s[36:37], s[2:3], 10
	s_mov_b64 s[2:3], 0x3000
	s_nop 2
	v_cvt_pk_bf16_f32 v76, v76, v77
	v_cvt_pk_bf16_f32 v77, v78, v79
	v_lshl_add_u64 v[78:79], v[100:101], 0, s[36:37]
	global_store_dwordx2 v[78:79], v[76:77], off
	s_waitcnt lgkmcnt(10)
	v_mfma_f32_16x16x32_bf16 v[76:79], v[200:203], v[224:227], 0
	ds_read_b64_tr_b16 v[250:251], v147 offset:27968
	ds_read2_b32 v[204:205], v164 offset1:1
	v_lshl_add_u64 v[106:107], v[106:107], 0, s[2:3]
	s_mov_b64 s[2:3], 0x6000
	s_addk_i32 s26, 0xc0
	v_mfma_f32_16x16x32_bf16 v[76:79], v[84:87], v[216:219], v[76:79]
	v_lshl_add_u64 v[108:109], v[108:109], 0, s[2:3]
	s_addk_i32 s27, 0xff40
	s_waitcnt lgkmcnt(11)
	v_mfma_f32_16x16x32_bf16 v[76:79], v[150:153], v[228:231], v[76:79]
	ds_read2_b32 v[206:207], v165 offset1:1
	s_mov_b64 s[2:3], 0x600
	v_lshl_add_u64 v[110:111], v[110:111], 0, s[2:3]
	s_cmpk_lt_u32 s24, 0x42
	s_nop 4
	v_cvt_pk_bf16_f32 v76, v76, v77
	v_cvt_pk_bf16_f32 v77, v78, v79
	v_lshl_add_u64 v[78:79], v[102:103], 0, s[36:37]
	global_store_dwordx2 v[78:79], v[76:77], off
	s_waitcnt lgkmcnt(11)
	v_pk_mul_f32 v[76:77], v[92:93], v[232:233]
	ds_read_b64_tr_b16 v[208:209], v146 offset:28000
	s_waitcnt lgkmcnt(11)
	v_pk_mul_f32 v[78:79], v[94:95], v[234:235]
	ds_read_b64_tr_b16 v[210:211], v147 offset:28000
	s_waitcnt lgkmcnt(9)
	v_mfma_f32_16x16x32_bf16 v[84:87], v[236:239], v[200:203], v[76:79]
	ds_read2_b32 v[212:213], v187 offset1:1
	ds_read2_b32 v[214:215], v186 offset1:1
	s_nop 2
	s_waitcnt lgkmcnt(9)
	v_pk_mul_f32 v[72:73], v[72:73], v[244:245]
	s_waitcnt lgkmcnt(8)
	v_pk_mul_f32 v[74:75], v[74:75], v[246:247]
	s_nop 1
	v_mfma_f32_16x16x32_bf16 v[76:79], v[240:243], v[200:203], v[72:75]
	s_nop 2
	s_waitcnt lgkmcnt(5)
	v_pk_mul_f32 v[80:81], v[80:81], v[204:205]
	s_waitcnt lgkmcnt(4)
	v_pk_mul_f32 v[82:83], v[82:83], v[206:207]
	s_nop 1
	v_mfma_f32_16x16x32_bf16 v[80:83], v[248:251], v[200:203], v[80:83]
	s_waitcnt lgkmcnt(1)
	v_pk_mul_f32 v[88:89], v[88:89], v[212:213]
	s_waitcnt lgkmcnt(0)
	v_pk_mul_f32 v[90:91], v[90:91], v[214:215]
	s_nop 1
	v_mfma_f32_16x16x32_bf16 v[72:75], v[208:211], v[200:203], v[88:91]
	s_cbranch_scc0 .LBB0_639

; DI void gla_scan_item(const P& p, int seq, unsigned char* smem) {
;     ...
;     auto storel = [&](const GlaRegs& R, int buf) {
;         unsigned char* base = smem + buf * BUFB;
;         bf16_t* sat = (bf16_t*)base; bf16_t* sqt = (bf16_t*)(base + 2560); bf16_t* sko = (bf16_t*)(base + 2560 + 4608); bf16_t* sv = (bf16_t*)(base + 2560 + 9216); float* sdc = (float*)(base + 2560 + 9216 + 8704);
;         { const int pos = tid >> 4, ch = tid & 15; *(u32x4*)(sv + pos * 136 + 8 * ch) = R.rv; }
;         { const int t2 = tid & 255, pos = t2 >> 3, ch = t2 & 7; *(u32x4*)((tid < 256 ? sqt : sko) + pos * 72 + 8 * ch) = R.rq; }
;         if (tid < 128) { const int i = tid >> 2, ch = tid & 3; *(u32x4*)(sat + i * 40 + 8 * ch) = R.ra; }
;     ...
;     auto compute = [&](int c) {
;         const unsigned char* base = smem + (c & 1) * BUFB;
;         const bf16_t* sat = (const bf16_t*)base; const bf16_t* sqt = (const bf16_t*)(base + 2560); const bf16_t* sko = (const bf16_t*)(base + 2560 + 4608); const bf16_t* sv = (const bf16_t*)(base + 2560 + 9216); const float* sdc = (const float*)(base + 2560 + 9216 + 8704);
;         const int dv0 = 16 * w;
;         const bf16x8 vb = tr2(sv + (8 * g + q4) * 136 + dv0 + 4 * p4, sv + (8 * g + 4 + q4) * 136 + dv0 + 4 * p4);
;         bf16x8 bs[2];
;         bs[0] = packacc(st[0], st[1]); bs[1] = packacc(st[2], st[3]);
; #pragma unroll
;         for (int mt = 0; mt < 2; ++mt) {
;             f32x4 acc = (f32x4){0.f, 0.f, 0.f, 0.f};
;             acc = mfma16(vb, ld8(sat + (16 * mt + l15) * 40 + 8 * g), acc);
; #pragma unroll
;             for (int ks = 0; ks < 2; ++ks) {
;                 const bf16_t* r0 = sqt + (16 * mt + l15) * 72 + 32 * ks + 4 * g;
;                 acc = mfma16(bs[ks], ld4x2(r0, r0 + 16), acc);
;             }
;             bf16_t* ob = OG + (size_t)prow(b, dir, 32 * c) * 512 + 128 * h;
;             u32x2 ov; ov.x = pk2(acc[0], acc[1]); ov.y = pk2(acc[2], acc[3]);
;             *(u32x2*)(ob + sgn * ((16 * mt + l15) * 512) + dv0 + 4 * g) = ov;
;         }
; #pragma unroll
;         for (int dt = 0; dt < 4; ++dt) {
;             const bf16x8 ak = tr2(sko + (8 * g + q4) * 72 + 16 * dt + 4 * p4, sko + (8 * g + 4 + q4) * 72 + 16 * dt + 4 * p4);
; #pragma unroll
;             for (int r = 0; r < 4; ++r) st[dt][r] *= sdc[16 * dt + 4 * g + r];
;             st[dt] = mfma16(ak, vb, st[dt]);
;         }
.LBB0_590:
	ds_read_b64_tr_b16 v[200:201], v123 offset:11776
	ds_read_b64_tr_b16 v[202:203], v124 offset:11776
	ds_read_b128 v[204:207], v125
	ds_read_b128 v[216:219], v127
	ds_read_b64_tr_b16 v[238:239], v144 offset:7168
	ds_read_b64_tr_b16 v[242:243], v144 offset:7200
	ds_read_b64_tr_b16 v[236:237], v143 offset:7168
	ds_read_b64_tr_b16 v[240:241], v143 offset:7200
	ds_read_b64_tr_b16 v[248:249], v143 offset:7232
	ds_read_b64_tr_b16 v[250:251], v144 offset:7232
	v_cvt_pk_bf16_f32 v96, v84, s0
	v_cvt_pk_bf16_f32 v99, v85, s0
	v_cvt_pk_bf16_f32 v151, v78, s0
	v_cvt_pk_bf16_f32 v152, v79, s0
	v_cvt_pk_bf16_f32 v97, v86, s0
	v_cvt_pk_bf16_f32 v134, v87, s0
	v_cvt_pk_bf16_f32 v98, v76, s0
	v_cvt_pk_bf16_f32 v135, v77, s0
	v_perm_b32 v96, v99, v96, s25
	v_perm_b32 v99, v152, v151, s25
	v_add_u32_e32 v152, 0x800, v126
	ds_read2_b64 v[208:211], v152 offset0:64 offset1:68
	ds_read2_b64 v[212:215], v152 offset0:72 offset1:76
	v_perm_b32 v98, v135, v98, s25
	v_perm_b32 v97, v134, v97, s25
	s_sub_i32 s4, s26, 64
	s_add_i32 s5, s26, 0xfffffec0
	s_add_i32 s6, s27, 0xa0
	s_add_i32 s7, s27, 0xfffff8a0
	s_waitcnt lgkmcnt(9)
	v_mfma_f32_16x16x32_bf16 v[92:95], v[200:203], v[204:207], 0
	s_and_b64 s[2:3], s[0:1], exec
	s_cselect_b32 s2, s4, s7
	v_cvt_pk_bf16_f32 v153, v80, s0
	v_cvt_pk_bf16_f32 v158, v81, s0
	v_cvt_pk_bf16_f32 v159, v82, s0
	v_cvt_pk_bf16_f32 v160, v83, s0
	v_cvt_pk_bf16_f32 v161, v72, s0
	v_cvt_pk_bf16_f32 v162, v73, s0
	v_cvt_pk_bf16_f32 v163, v74, s0
	v_cvt_pk_bf16_f32 v164, v75, s0
	s_add_i32 s4, s2, s22
	s_and_b64 s[2:3], s[0:1], exec
	s_waitcnt lgkmcnt(1)
	v_mfma_f32_16x16x32_bf16 v[92:95], v[96:99], v[208:211], v[92:95]
	ds_read_b64_tr_b16 v[208:209], v143 offset:7264
	ds_read_b64_tr_b16 v[210:211], v144 offset:7264
	v_perm_b32 v156, v162, v161, s25
	v_perm_b32 v155, v160, v159, s25
	v_perm_b32 v154, v158, v153, s25
	v_perm_b32 v157, v164, v163, s25
	s_cselect_b32 s2, s5, s6
	s_add_i32 s5, s2, s21
	s_cmp_lt_u32 s24, 8
	s_cselect_b64 s[36:37], -1, 0
	s_waitcnt lgkmcnt(2)
	v_mfma_f32_16x16x32_bf16 v[92:95], v[154:157], v[212:215], v[92:95]
	s_and_b64 s[2:3], s[36:37], exec
	s_cselect_b32 s2, s4, s5
	s_ashr_i32 s3, s2, 31
	s_lshl_b64 s[42:43], s[2:3], 10
	v_add_u32_e32 v151, 0x800, v142
	ds_read2_b64 v[224:227], v151 offset0:64 offset1:68
	ds_read2_b64 v[228:231], v151 offset0:72 offset1:76
	s_nop 2
	v_cvt_pk_bf16_f32 v92, v92, v93
	v_cvt_pk_bf16_f32 v93, v94, v95
	v_lshl_add_u64 v[94:95], v[100:101], 0, s[42:43]
	global_store_dwordx2 v[94:95], v[92:93], off
	v_mfma_f32_16x16x32_bf16 v[92:95], v[200:203], v[216:219], 0
	v_add_u32_e32 v153, 0x5000, v145
	ds_read2_b32 v[232:233], v153 offset1:1
	s_waitcnt lgkmcnt(2)
	v_mfma_f32_16x16x32_bf16 v[92:95], v[96:99], v[224:227], v[92:95]
	v_add_u32_e32 v158, 0x5040, v145
	ds_read2_b32 v[244:245], v158 offset1:1
	v_add_u32_e32 v161, 0x50c0, v145
	ds_read2_b32 v[212:213], v161 offset1:1
	s_waitcnt lgkmcnt(3)
	v_mfma_f32_16x16x32_bf16 v[92:95], v[154:157], v[228:231], v[92:95]
	v_add_u32_e32 v156, 0x5008, v145
	ds_read2_b32 v[234:235], v156 offset1:1
	v_add_u32_e32 v157, 0x5048, v145
	ds_read2_b32 v[246:247], v157 offset1:1
	v_add_u32_e32 v154, 0x5080, v145
	ds_read2_b32 v[204:205], v154 offset1:1
	s_nop 4
	v_cvt_pk_bf16_f32 v92, v92, v93
	v_cvt_pk_bf16_f32 v93, v94, v95
	v_lshl_add_u64 v[94:95], v[102:103], 0, s[42:43]
	global_store_dwordx2 v[94:95], v[92:93], off
	v_add_u32_e32 v155, 0x5088, v145
	ds_read2_b32 v[206:207], v155 offset1:1
	v_add_u32_e32 v160, 0x50c8, v145
	ds_read2_b32 v[214:215], v160 offset1:1
	s_waitcnt lgkmcnt(7)
	v_pk_mul_f32 v[84:85], v[84:85], v[232:233]
	s_waitcnt lgkmcnt(4)
	v_pk_mul_f32 v[86:87], v[86:87], v[234:235]
	s_nop 1
	v_mfma_f32_16x16x32_bf16 v[84:87], v[236:239], v[200:203], v[84:87]
	v_pk_mul_f32 v[76:77], v[76:77], v[244:245]
	s_waitcnt lgkmcnt(3)
	v_pk_mul_f32 v[78:79], v[78:79], v[246:247]
	s_nop 1
	v_mfma_f32_16x16x32_bf16 v[76:79], v[240:243], v[200:203], v[76:79]
	s_waitcnt lgkmcnt(2)
	v_pk_mul_f32 v[80:81], v[80:81], v[204:205]
	s_waitcnt lgkmcnt(1)
	v_pk_mul_f32 v[82:83], v[82:83], v[206:207]
	s_nop 1
	v_mfma_f32_16x16x32_bf16 v[80:83], v[248:251], v[200:203], v[80:83]
	s_waitcnt vmcnt(11)
	ds_write_b128 v121, v[12:15] offset:32512
	s_waitcnt vmcnt(10)
	ds_write_b128 v122, v[20:23] offset:20736
	v_pk_mul_f32 v[72:73], v[72:73], v[212:213]
	s_waitcnt lgkmcnt(2)
	v_pk_mul_f32 v[74:75], v[74:75], v[214:215]
	s_nop 1
	v_mfma_f32_16x16x32_bf16 v[72:75], v[208:211], v[200:203], v[72:75]
	s_waitcnt lgkmcnt(0)
	s_and_saveexec_b64 s[42:43], s[38:39]
	ds_write_b128 v148, v[16:19] offset:20736
	s_or_b64 exec, exec, s[42:43]
	s_and_saveexec_b64 s[42:43], s[40:41]
	ds_write_b32 v149, v116 offset:40704
	s_or_b64 exec, exec, s[42:43]
	s_cmp_gt_u32 s24, 64
	s_waitcnt lgkmcnt(0)
	s_barrier
	s_cbranch_scc1 .LBB0_600
	v_add_u32_e32 v12, 0xa0, v150
	s_movk_i32 s2, 0x100
	v_cmp_gt_i32_e32 vcc, s2, v12
	v_add_u32_e32 v13, 0xffffffa0, v150
	v_mov_b32_e32 v15, s22
	v_cndmask_b32_e32 v14, v174, v175, vcc
	v_add3_u32 v14, v132, v14, s27
	v_cndmask_b32_e32 v12, v13, v12, vcc
	v_mov_b32_e32 v13, s21
	v_add_u32_e32 v14, 0xfffff6c1, v14
	v_cndmask_b32_e32 v13, v13, v15, vcc
	v_cndmask_b32_e64 v12, v14, v12, s[0:1]
	v_add_u32_e32 v12, v12, v13
	s_movk_i32 s2, 0x3800
	v_add_co_u32_e32 v20, vcc, 0x7000, v112
	v_mad_i64_i32 v[12:13], s[2:3], v12, s2, v[104:105]
	s_nop 0
	v_addc_co_u32_e32 v21, vcc, 0, v113, vcc
	global_load_dwordx4 v[12:15], v[12:13], off offset:1024
	s_nop 0
	global_load_dwordx4 v[20:23], v[20:21], off nt
	s_and_saveexec_b64 s[42:43], s[38:39]
	s_cbranch_execz .LBB0_597
	v_lshl_add_u64 v[16:17], v[106:107], 0, s[44:45]
	v_add_co_u32_e32 v16, vcc, 0x1283f000, v16
	s_nop 1
	v_addc_co_u32_e32 v17, vcc, 0, v17, vcc
	global_load_dwordx4 v[16:19], v[16:17], off offset:2048 nt

; DI void gla_scan_item(const P& p, int seq, unsigned char* smem) {
;     ...
;     auto storel = [&](const GlaRegs& R, int buf) {
;         unsigned char* base = smem + buf * BUFB;
;         bf16_t* sat = (bf16_t*)base; bf16_t* sqt = (bf16_t*)(base + 2560); bf16_t* sko = (bf16_t*)(base + 2560 + 4608); bf16_t* sv = (bf16_t*)(base + 2560 + 9216); float* sdc = (float*)(base + 2560 + 9216 + 8704);
;         { const int pos = tid >> 4, ch = tid & 15; *(u32x4*)(sv + pos * 136 + 8 * ch) = R.rv; }
;         { const int t2 = tid & 255, pos = t2 >> 3, ch = t2 & 7; *(u32x4*)((tid < 256 ? sqt : sko) + pos * 72 + 8 * ch) = R.rq; }
;         if (tid < 128) { const int i = tid >> 2, ch = tid & 3; *(u32x4*)(sat + i * 40 + 8 * ch) = R.ra; }
;     ...
;     auto compute = [&](int c) {
;         const unsigned char* base = smem + (c & 1) * BUFB;
;         const bf16_t* sat = (const bf16_t*)base; const bf16_t* sqt = (const bf16_t*)(base + 2560); const bf16_t* sko = (const bf16_t*)(base + 2560 + 4608); const bf16_t* sv = (const bf16_t*)(base + 2560 + 9216); const float* sdc = (const float*)(base + 2560 + 9216 + 8704);
;         const int dv0 = 16 * w;
;         const bf16x8 vb = tr2(sv + (8 * g + q4) * 136 + dv0 + 4 * p4, sv + (8 * g + 4 + q4) * 136 + dv0 + 4 * p4);
;         bf16x8 bs[2];
;         bs[0] = packacc(st[0], st[1]); bs[1] = packacc(st[2], st[3]);
; #pragma unroll
;         for (int mt = 0; mt < 2; ++mt) {
;             f32x4 acc = (f32x4){0.f, 0.f, 0.f, 0.f};
;             acc = mfma16(vb, ld8(sat + (16 * mt + l15) * 40 + 8 * g), acc);
; #pragma unroll
;             for (int ks = 0; ks < 2; ++ks) {
;                 const bf16_t* r0 = sqt + (16 * mt + l15) * 72 + 32 * ks + 4 * g;
;                 acc = mfma16(bs[ks], ld4x2(r0, r0 + 16), acc);
;             }
;             bf16_t* ob = OG + (size_t)prow(b, dir, 32 * c) * 512 + 128 * h;
;             u32x2 ov; ov.x = pk2(acc[0], acc[1]); ov.y = pk2(acc[2], acc[3]);
;             *(u32x2*)(ob + sgn * ((16 * mt + l15) * 512) + dv0 + 4 * g) = ov;
;         }
; #pragma unroll
;         for (int dt = 0; dt < 4; ++dt) {
;             const bf16x8 ak = tr2(sko + (8 * g + q4) * 72 + 16 * dt + 4 * p4, sko + (8 * g + 4 + q4) * 72 + 16 * dt + 4 * p4);
; #pragma unroll
;             for (int r = 0; r < 4; ++r) st[dt][r] *= sdc[16 * dt + 4 * g + r];
;             st[dt] = mfma16(ak, vb, st[dt]);
;         }
.LBB0_600:
	ds_read_b64_tr_b16 v[200:201], v123 offset:32512
	ds_read_b64_tr_b16 v[202:203], v124 offset:32512
	ds_read_b128 v[204:207], v125 offset:20736
	ds_read_b128 v[216:219], v127 offset:20736
	ds_read_b64_tr_b16 v[238:239], v147 offset:27904
	ds_read_b64_tr_b16 v[242:243], v147 offset:27936
	ds_read_b64_tr_b16 v[236:237], v146 offset:27904
	ds_read_b64_tr_b16 v[240:241], v146 offset:27936
	ds_read_b64_tr_b16 v[248:249], v146 offset:27968
	ds_read_b64_tr_b16 v[250:251], v147 offset:27968
	v_cvt_pk_bf16_f32 v96, v84, s0
	v_cvt_pk_bf16_f32 v99, v85, s0
	v_cvt_pk_bf16_f32 v159, v78, s0
	v_cvt_pk_bf16_f32 v162, v79, s0
	v_cvt_pk_bf16_f32 v97, v86, s0
	v_cvt_pk_bf16_f32 v134, v87, s0
	v_cvt_pk_bf16_f32 v98, v76, s0
	v_cvt_pk_bf16_f32 v135, v77, s0
	v_perm_b32 v96, v99, v96, s25
	v_perm_b32 v99, v162, v159, s25
	v_add_u32_e32 v159, 0x5800, v126
	ds_read2_b64 v[208:211], v159 offset0:96 offset1:100
	ds_read2_b64 v[212:215], v159 offset0:104 offset1:108
	v_perm_b32 v98, v135, v98, s25
	v_perm_b32 v97, v134, v97, s25
	s_waitcnt lgkmcnt(9)
	v_mfma_f32_16x16x32_bf16 v[88:91], v[200:203], v[204:207], 0
	s_sub_i32 s4, s26, 32
	s_add_i32 s5, s26, 0xfffffee0
	s_add_i32 s6, s27, 0x80
	s_add_i32 s7, s27, 0xfffff880
	v_cvt_pk_bf16_f32 v183, v80, s0
	v_cvt_pk_bf16_f32 v184, v81, s0
	v_cvt_pk_bf16_f32 v185, v82, s0
	v_cvt_pk_bf16_f32 v186, v83, s0
	v_cvt_pk_bf16_f32 v187, v72, s0
	v_cvt_pk_bf16_f32 v188, v73, s0
	v_cvt_pk_bf16_f32 v189, v74, s0
	v_cvt_pk_bf16_f32 v190, v75, s0
	s_and_b64 s[2:3], s[0:1], exec
	s_waitcnt lgkmcnt(1)
	v_mfma_f32_16x16x32_bf16 v[162:165], v[96:99], v[208:211], v[88:91]
	ds_read_b64_tr_b16 v[208:209], v146 offset:28000
	ds_read_b64_tr_b16 v[210:211], v147 offset:28000
	s_cselect_b32 s2, s4, s7
	s_add_i32 s4, s2, s22
	s_and_b64 s[2:3], s[0:1], exec
	v_perm_b32 v90, v188, v187, s25
	v_perm_b32 v89, v186, v185, s25
	v_perm_b32 v88, v184, v183, s25
	v_perm_b32 v91, v190, v189, s25
	s_cselect_b32 s2, s5, s6
	s_add_i32 s5, s2, s21
	s_waitcnt lgkmcnt(2)
	v_mfma_f32_16x16x32_bf16 v[162:165], v[88:91], v[212:215], v[162:165]
	s_and_b64 s[2:3], s[36:37], exec
	s_cselect_b32 s2, s4, s5
	s_ashr_i32 s3, s2, 31
	s_lshl_b64 s[36:37], s[2:3], 10
	s_nop 3
	v_cvt_pk_bf16_f32 v134, v162, v163
	v_cvt_pk_bf16_f32 v135, v164, v165
	v_lshl_add_u64 v[162:163], v[100:101], 0, s[36:37]
	global_store_dwordx2 v[162:163], v[134:135], off
	v_mfma_f32_16x16x32_bf16 v[184:187], v[200:203], v[216:219], 0
	v_add_u32_e32 v162, 0x5800, v142
	ds_read2_b64 v[224:227], v162 offset0:96 offset1:100
	ds_read2_b64 v[228:231], v162 offset0:104 offset1:108
	v_add_u32_e32 v163, 0xa100, v145
	ds_read2_b32 v[232:233], v163 offset1:1
	s_waitcnt lgkmcnt(2)
	v_mfma_f32_16x16x32_bf16 v[96:99], v[96:99], v[224:227], v[184:187]
	s_nop 2
	v_add_u32_e32 v183, 0xa108, v145
	ds_read2_b32 v[234:235], v183 offset1:1
	v_add_u32_e32 v164, 0xa180, v145
	ds_read2_b32 v[204:205], v164 offset1:1
	s_waitcnt lgkmcnt(3)
	v_mfma_f32_16x16x32_bf16 v[88:91], v[88:91], v[228:231], v[96:99]
	v_add_u32_e32 v185, 0xa140, v145
	ds_read2_b32 v[244:245], v185 offset1:1
	v_add_u32_e32 v184, 0xa148, v145
	ds_read2_b32 v[246:247], v184 offset1:1
	v_add_u32_e32 v165, 0xa188, v145
	ds_read2_b32 v[206:207], v165 offset1:1
	s_nop 4
	v_cvt_pk_bf16_f32 v88, v88, v89
	v_cvt_pk_bf16_f32 v89, v90, v91
	v_lshl_add_u64 v[90:91], v[102:103], 0, s[36:37]
	global_store_dwordx2 v[90:91], v[88:89], off
	v_add_u32_e32 v187, 0xa1c0, v145
	ds_read2_b32 v[212:213], v187 offset1:1
	v_add_u32_e32 v186, 0xa1c8, v145
	ds_read2_b32 v[214:215], v186 offset1:1
	s_waitcnt lgkmcnt(7)
	v_pk_mul_f32 v[84:85], v[84:85], v[232:233]
	s_waitcnt lgkmcnt(6)
	v_pk_mul_f32 v[86:87], v[86:87], v[234:235]
	s_nop 1
	v_mfma_f32_16x16x32_bf16 v[88:91], v[236:239], v[200:203], v[84:87]
	s_nop 2
	s_waitcnt lgkmcnt(4)
	v_pk_mul_f32 v[76:77], v[76:77], v[244:245]
	s_waitcnt lgkmcnt(3)
	v_pk_mul_f32 v[78:79], v[78:79], v[246:247]
	s_nop 1
	v_mfma_f32_16x16x32_bf16 v[84:87], v[240:243], v[200:203], v[76:79]
	s_nop 2
	v_pk_mul_f32 v[80:81], v[80:81], v[204:205]
	s_waitcnt lgkmcnt(2)
	v_pk_mul_f32 v[82:83], v[82:83], v[206:207]
	s_nop 1
	v_mfma_f32_16x16x32_bf16 v[76:79], v[248:251], v[200:203], v[80:83]
	s_nop 2
	s_waitcnt vmcnt(11)
	ds_write_b128 v121, v[24:27] offset:11776
	s_waitcnt vmcnt(10)
	ds_write_b128 v122, v[32:35]
	s_waitcnt lgkmcnt(3)
	v_pk_mul_f32 v[72:73], v[72:73], v[212:213]
	s_waitcnt lgkmcnt(2)
	v_pk_mul_f32 v[74:75], v[74:75], v[214:215]
	s_nop 1
	v_mfma_f32_16x16x32_bf16 v[80:83], v[208:211], v[200:203], v[72:75]
	s_waitcnt lgkmcnt(0)
	s_and_saveexec_b64 s[36:37], s[38:39]
	ds_write_b128 v148, v[28:31]
	s_or_b64 exec, exec, s[36:37]
	s_and_saveexec_b64 s[36:37], s[40:41]
	ds_write_b32 v149, v117 offset:19968
	s_or_b64 exec, exec, s[36:37]
	s_cmp_gt_u32 s24, 63
	s_waitcnt lgkmcnt(0)
	s_barrier
	s_cbranch_scc1 .LBB0_610
	v_add_u32_e32 v24, 0xc0, v150
	s_movk_i32 s2, 0x100
	v_cmp_gt_i32_e32 vcc, s2, v24
	v_subrev_u32_e32 v25, 64, v150
	v_mov_b32_e32 v27, s22
	v_cndmask_b32_e32 v26, v174, v175, vcc
	v_add3_u32 v26, v132, v26, s27
	v_cndmask_b32_e32 v24, v25, v24, vcc
	v_mov_b32_e32 v25, s21
	v_add_u32_e32 v26, 0xfffff6a1, v26
	v_cndmask_b32_e32 v25, v25, v27, vcc
	v_cndmask_b32_e64 v24, v26, v24, s[0:1]
	v_add_u32_e32 v24, v24, v25
	s_movk_i32 s2, 0x3800
	v_add_co_u32_e32 v32, vcc, 0x8000, v112
	v_mad_i64_i32 v[24:25], s[2:3], v24, s2, v[104:105]
	s_nop 0
	v_addc_co_u32_e32 v33, vcc, 0, v113, vcc
	global_load_dwordx4 v[24:27], v[24:25], off offset:1024
	s_nop 0
	global_load_dwordx4 v[32:35], v[32:33], off nt
	s_and_saveexec_b64 s[36:37], s[38:39]
	s_cbranch_execz .LBB0_607
	v_lshl_add_u64 v[28:29], v[106:107], 0, s[44:45]
	v_add_co_u32_e32 v28, vcc, 0x12840000, v28
	s_nop 1
	v_addc_co_u32_e32 v29, vcc, 0, v29, vcc
	global_load_dwordx4 v[28:31], v[28:29], off nt

; DI void gla_scan_item(const P& p, int seq, unsigned char* smem) {
;     ...
;     auto storel = [&](const GlaRegs& R, int buf) {
;         unsigned char* base = smem + buf * BUFB;
;         bf16_t* sat = (bf16_t*)base; bf16_t* sqt = (bf16_t*)(base + 2560); bf16_t* sko = (bf16_t*)(base + 2560 + 4608); bf16_t* sv = (bf16_t*)(base + 2560 + 9216); float* sdc = (float*)(base + 2560 + 9216 + 8704);
;         { const int pos = tid >> 4, ch = tid & 15; *(u32x4*)(sv + pos * 136 + 8 * ch) = R.rv; }
;         { const int t2 = tid & 255, pos = t2 >> 3, ch = t2 & 7; *(u32x4*)((tid < 256 ? sqt : sko) + pos * 72 + 8 * ch) = R.rq; }
;         if (tid < 128) { const int i = tid >> 2, ch = tid & 3; *(u32x4*)(sat + i * 40 + 8 * ch) = R.ra; }
;     ...
;     auto compute = [&](int c) {
;         const unsigned char* base = smem + (c & 1) * BUFB;
;         const bf16_t* sat = (const bf16_t*)base; const bf16_t* sqt = (const bf16_t*)(base + 2560); const bf16_t* sko = (const bf16_t*)(base + 2560 + 4608); const bf16_t* sv = (const bf16_t*)(base + 2560 + 9216); const float* sdc = (const float*)(base + 2560 + 9216 + 8704);
;         const int dv0 = 16 * w;
;         const bf16x8 vb = tr2(sv + (8 * g + q4) * 136 + dv0 + 4 * p4, sv + (8 * g + 4 + q4) * 136 + dv0 + 4 * p4);
;         bf16x8 bs[2];
;         bs[0] = packacc(st[0], st[1]); bs[1] = packacc(st[2], st[3]);
; #pragma unroll
;         for (int mt = 0; mt < 2; ++mt) {
;             f32x4 acc = (f32x4){0.f, 0.f, 0.f, 0.f};
;             acc = mfma16(vb, ld8(sat + (16 * mt + l15) * 40 + 8 * g), acc);
; #pragma unroll
;             for (int ks = 0; ks < 2; ++ks) {
;                 const bf16_t* r0 = sqt + (16 * mt + l15) * 72 + 32 * ks + 4 * g;
;                 acc = mfma16(bs[ks], ld4x2(r0, r0 + 16), acc);
;             }
;             bf16_t* ob = OG + (size_t)prow(b, dir, 32 * c) * 512 + 128 * h;
;             u32x2 ov; ov.x = pk2(acc[0], acc[1]); ov.y = pk2(acc[2], acc[3]);
;             *(u32x2*)(ob + sgn * ((16 * mt + l15) * 512) + dv0 + 4 * g) = ov;
;         }
; #pragma unroll
;         for (int dt = 0; dt < 4; ++dt) {
;             const bf16x8 ak = tr2(sko + (8 * g + q4) * 72 + 16 * dt + 4 * p4, sko + (8 * g + 4 + q4) * 72 + 16 * dt + 4 * p4);
; #pragma unroll
;             for (int r = 0; r < 4; ++r) st[dt][r] *= sdc[16 * dt + 4 * g + r];
;             st[dt] = mfma16(ak, vb, st[dt]);
;         }
.LBB0_610:
	ds_read_b64_tr_b16 v[200:201], v123 offset:11776
	ds_read_b64_tr_b16 v[202:203], v124 offset:11776
	ds_read_b128 v[204:207], v125
	ds_read2_b64 v[208:211], v152 offset0:64 offset1:68
	ds_read2_b64 v[212:215], v152 offset0:72 offset1:76
	ds_read2_b64 v[216:219], v151 offset0:64 offset1:68
	ds_read_b128 v[224:227], v127
	ds_read2_b64 v[228:231], v151 offset0:72 offset1:76
	ds_read2_b32 v[232:233], v153 offset1:1
	ds_read2_b32 v[234:235], v156 offset1:1
	ds_read_b64_tr_b16 v[238:239], v144 offset:7168
	ds_read_b64_tr_b16 v[242:243], v144 offset:7200
	v_cvt_pk_bf16_f32 v96, v88, s0
	v_cvt_pk_bf16_f32 v99, v89, s0
	v_cvt_pk_bf16_f32 v97, v90, s0
	v_cvt_pk_bf16_f32 v134, v91, s0
	v_cvt_pk_bf16_f32 v98, v84, s0
	v_cvt_pk_bf16_f32 v135, v85, s0
	v_cvt_pk_bf16_f32 v188, v86, s0
	v_cvt_pk_bf16_f32 v189, v87, s0
	v_perm_b32 v98, v135, v98, s25
	v_perm_b32 v97, v134, v97, s25
	v_perm_b32 v96, v99, v96, s25
	v_perm_b32 v99, v189, v188, s25
	s_waitcnt lgkmcnt(9)
	v_mfma_f32_16x16x32_bf16 v[72:75], v[200:203], v[204:207], 0
	ds_read_b64_tr_b16 v[236:237], v143 offset:7168
	ds_read_b64_tr_b16 v[240:241], v143 offset:7200
	ds_read2_b32 v[244:245], v158 offset1:1
	s_add_i32 s4, s26, 0xffffff00
	s_add_i32 s5, s27, 0x60
	s_add_i32 s6, s27, 0xfffff860
	v_cvt_pk_bf16_f32 v192, v76, s0
	v_cvt_pk_bf16_f32 v193, v77, s0
	v_cvt_pk_bf16_f32 v194, v78, s0
	v_cvt_pk_bf16_f32 v195, v79, s0
	v_cvt_pk_bf16_f32 v196, v80, s0
	v_cvt_pk_bf16_f32 v197, v81, s0
	v_cvt_pk_bf16_f32 v198, v82, s0
	v_cvt_pk_bf16_f32 v199, v83, s0
	s_and_b64 s[2:3], s[0:1], exec
	s_cselect_b32 s2, s26, s6
	s_waitcnt lgkmcnt(11)
	v_mfma_f32_16x16x32_bf16 v[72:75], v[96:99], v[208:211], v[72:75]
	ds_read2_b32 v[246:247], v157 offset1:1
	v_perm_b32 v190, v197, v196, s25
	v_perm_b32 v189, v195, v194, s25
	v_perm_b32 v188, v193, v192, s25
	v_perm_b32 v191, v199, v198, s25
	s_add_i32 s6, s2, s22
	s_and_b64 s[2:3], s[0:1], exec
	s_cselect_b32 s2, s4, s5
	s_add_i32 s2, s2, s21
	s_cmp_lt_u32 s24, 6
	s_waitcnt lgkmcnt(11)
	v_mfma_f32_16x16x32_bf16 v[72:75], v[188:191], v[212:215], v[72:75]
	ds_read_b64_tr_b16 v[248:249], v143 offset:7232
	s_cselect_b32 s2, s6, s2
	s_ashr_i32 s3, s2, 31
	s_lshl_b64 s[36:37], s[2:3], 10
	s_nop 3
	v_cvt_pk_bf16_f32 v72, v72, v73
	v_cvt_pk_bf16_f32 v73, v74, v75
	v_lshl_add_u64 v[74:75], v[100:101], 0, s[36:37]
	global_store_dwordx2 v[74:75], v[72:73], off
	s_waitcnt lgkmcnt(10)
	v_mfma_f32_16x16x32_bf16 v[72:75], v[200:203], v[224:227], 0
	ds_read_b64_tr_b16 v[250:251], v144 offset:7232
	ds_read2_b32 v[204:205], v154 offset1:1
	v_mfma_f32_16x16x32_bf16 v[72:75], v[96:99], v[216:219], v[72:75]
	s_waitcnt lgkmcnt(11)
	v_mfma_f32_16x16x32_bf16 v[72:75], v[188:191], v[228:231], v[72:75]
	ds_read2_b32 v[206:207], v155 offset1:1
	s_nop 7
	v_cvt_pk_bf16_f32 v72, v72, v73
	v_cvt_pk_bf16_f32 v73, v74, v75
	v_lshl_add_u64 v[74:75], v[102:103], 0, s[36:37]
	global_store_dwordx2 v[74:75], v[72:73], off
	s_waitcnt lgkmcnt(11)
	v_pk_mul_f32 v[72:73], v[88:89], v[232:233]
	ds_read_b64_tr_b16 v[208:209], v143 offset:7264
	s_waitcnt lgkmcnt(11)
	v_pk_mul_f32 v[74:75], v[90:91], v[234:235]
	ds_read_b64_tr_b16 v[210:211], v144 offset:7264
	s_waitcnt lgkmcnt(9)
	v_mfma_f32_16x16x32_bf16 v[88:91], v[236:239], v[200:203], v[72:75]
	ds_read2_b32 v[212:213], v161 offset1:1
	ds_read2_b32 v[214:215], v160 offset1:1
	s_nop 2
	s_waitcnt lgkmcnt(9)
	v_pk_mul_f32 v[72:73], v[84:85], v[244:245]
	s_waitcnt lgkmcnt(8)
	v_pk_mul_f32 v[74:75], v[86:87], v[246:247]
	s_nop 1
	v_mfma_f32_16x16x32_bf16 v[72:75], v[240:243], v[200:203], v[72:75]
	s_waitcnt lgkmcnt(5)
	v_pk_mul_f32 v[76:77], v[76:77], v[204:205]
	s_waitcnt lgkmcnt(4)
	v_pk_mul_f32 v[78:79], v[78:79], v[206:207]
	s_nop 1
	v_mfma_f32_16x16x32_bf16 v[76:79], v[248:251], v[200:203], v[76:79]
	s_waitcnt vmcnt(11)
	ds_write_b128 v121, v[36:39] offset:32512
	s_waitcnt vmcnt(10)
	ds_write_b128 v122, v[44:47] offset:20736
	s_waitcnt lgkmcnt(3)
	v_pk_mul_f32 v[80:81], v[80:81], v[212:213]
	s_waitcnt lgkmcnt(2)
	v_pk_mul_f32 v[82:83], v[82:83], v[214:215]
	s_nop 1
	v_mfma_f32_16x16x32_bf16 v[80:83], v[208:211], v[200:203], v[80:83]
	s_waitcnt lgkmcnt(0)
	s_and_saveexec_b64 s[36:37], s[38:39]
	ds_write_b128 v148, v[40:43] offset:20736
	s_or_b64 exec, exec, s[36:37]
	s_and_saveexec_b64 s[36:37], s[40:41]
	ds_write_b32 v149, v118 offset:40704
	s_or_b64 exec, exec, s[36:37]
	s_cmp_gt_u32 s24, 62
	s_waitcnt lgkmcnt(0)
	s_barrier
	s_cbranch_scc1 .LBB0_620
	v_add_u32_e32 v36, 0xe0, v150
	s_movk_i32 s2, 0x100
	v_cmp_gt_i32_e32 vcc, s2, v36
	v_subrev_u32_e32 v37, 32, v150
	v_mov_b32_e32 v39, s22
	v_cndmask_b32_e32 v38, v174, v175, vcc
	v_add3_u32 v38, v132, v38, s27
	v_cndmask_b32_e32 v36, v37, v36, vcc
	v_mov_b32_e32 v37, s21
	v_add_u32_e32 v38, 0xfffff681, v38
	v_cndmask_b32_e32 v37, v37, v39, vcc
	v_cndmask_b32_e64 v36, v38, v36, s[0:1]
	v_add_u32_e32 v36, v36, v37
	s_movk_i32 s2, 0x3800
	v_add_co_u32_e32 v44, vcc, 0x9000, v112
	v_mad_i64_i32 v[36:37], s[2:3], v36, s2, v[104:105]
	s_nop 0
	v_addc_co_u32_e32 v45, vcc, 0, v113, vcc
	global_load_dwordx4 v[36:39], v[36:37], off offset:1024
	s_nop 0
	global_load_dwordx4 v[44:47], v[44:45], off nt
	s_and_saveexec_b64 s[36:37], s[38:39]
	s_cbranch_execz .LBB0_617
	v_lshl_add_u64 v[40:41], v[106:107], 0, s[44:45]
	v_add_co_u32_e32 v40, vcc, 0x12840000, v40
	s_nop 1
	v_addc_co_u32_e32 v41, vcc, 0, v41, vcc
	global_load_dwordx4 v[40:43], v[40:41], off offset:2048 nt

; DI void gla_scan_item(const P& p, int seq, unsigned char* smem) {
;     ...
;     auto storel = [&](const GlaRegs& R, int buf) {
;         unsigned char* base = smem + buf * BUFB;
;         bf16_t* sat = (bf16_t*)base; bf16_t* sqt = (bf16_t*)(base + 2560); bf16_t* sko = (bf16_t*)(base + 2560 + 4608); bf16_t* sv = (bf16_t*)(base + 2560 + 9216); float* sdc = (float*)(base + 2560 + 9216 + 8704);
;         { const int pos = tid >> 4, ch = tid & 15; *(u32x4*)(sv + pos * 136 + 8 * ch) = R.rv; }
;         { const int t2 = tid & 255, pos = t2 >> 3, ch = t2 & 7; *(u32x4*)((tid < 256 ? sqt : sko) + pos * 72 + 8 * ch) = R.rq; }
;         if (tid < 128) { const int i = tid >> 2, ch = tid & 3; *(u32x4*)(sat + i * 40 + 8 * ch) = R.ra; }
;     ...
;     auto compute = [&](int c) {
;         const unsigned char* base = smem + (c & 1) * BUFB;
;         const bf16_t* sat = (const bf16_t*)base; const bf16_t* sqt = (const bf16_t*)(base + 2560); const bf16_t* sko = (const bf16_t*)(base + 2560 + 4608); const bf16_t* sv = (const bf16_t*)(base + 2560 + 9216); const float* sdc = (const float*)(base + 2560 + 9216 + 8704);
;         const int dv0 = 16 * w;
;         const bf16x8 vb = tr2(sv + (8 * g + q4) * 136 + dv0 + 4 * p4, sv + (8 * g + 4 + q4) * 136 + dv0 + 4 * p4);
;         bf16x8 bs[2];
;         bs[0] = packacc(st[0], st[1]); bs[1] = packacc(st[2], st[3]);
; #pragma unroll
;         for (int mt = 0; mt < 2; ++mt) {
;             f32x4 acc = (f32x4){0.f, 0.f, 0.f, 0.f};
;             acc = mfma16(vb, ld8(sat + (16 * mt + l15) * 40 + 8 * g), acc);
; #pragma unroll
;             for (int ks = 0; ks < 2; ++ks) {
;                 const bf16_t* r0 = sqt + (16 * mt + l15) * 72 + 32 * ks + 4 * g;
;                 acc = mfma16(bs[ks], ld4x2(r0, r0 + 16), acc);
;             }
;             bf16_t* ob = OG + (size_t)prow(b, dir, 32 * c) * 512 + 128 * h;
;             u32x2 ov; ov.x = pk2(acc[0], acc[1]); ov.y = pk2(acc[2], acc[3]);
;             *(u32x2*)(ob + sgn * ((16 * mt + l15) * 512) + dv0 + 4 * g) = ov;
;         }
; #pragma unroll
;         for (int dt = 0; dt < 4; ++dt) {
;             const bf16x8 ak = tr2(sko + (8 * g + q4) * 72 + 16 * dt + 4 * p4, sko + (8 * g + 4 + q4) * 72 + 16 * dt + 4 * p4);
; #pragma unroll
;             for (int r = 0; r < 4; ++r) st[dt][r] *= sdc[16 * dt + 4 * g + r];
;             st[dt] = mfma16(ak, vb, st[dt]);
;         }
;     };
.LBB0_620:
	ds_read_b64_tr_b16 v[200:201], v123 offset:32512
	ds_read_b64_tr_b16 v[202:203], v124 offset:32512
	ds_read_b128 v[204:207], v125 offset:20736
	ds_read2_b64 v[208:211], v159 offset0:96 offset1:100
	ds_read2_b64 v[212:215], v159 offset0:104 offset1:108
	ds_read2_b64 v[216:219], v162 offset0:96 offset1:100
	ds_read_b128 v[224:227], v127 offset:20736
	ds_read2_b64 v[228:231], v162 offset0:104 offset1:108
	ds_read2_b32 v[232:233], v163 offset1:1
	ds_read2_b32 v[234:235], v183 offset1:1
	ds_read_b64_tr_b16 v[238:239], v147 offset:27904
	ds_read_b64_tr_b16 v[242:243], v147 offset:27936
	v_cvt_pk_bf16_f32 v96, v88, s0
	v_cvt_pk_bf16_f32 v99, v89, s0
	v_cvt_pk_bf16_f32 v97, v90, s0
	v_cvt_pk_bf16_f32 v134, v91, s0
	v_cvt_pk_bf16_f32 v98, v72, s0
	v_cvt_pk_bf16_f32 v135, v73, s0
	v_cvt_pk_bf16_f32 v188, v74, s0
	v_cvt_pk_bf16_f32 v189, v75, s0
	v_perm_b32 v98, v135, v98, s25
	v_perm_b32 v97, v134, v97, s25
	v_perm_b32 v96, v99, v96, s25
	v_perm_b32 v99, v189, v188, s25
	s_waitcnt lgkmcnt(9)
	v_mfma_f32_16x16x32_bf16 v[92:95], v[200:203], v[204:207], 0
	ds_read_b64_tr_b16 v[236:237], v146 offset:27904
	ds_read_b64_tr_b16 v[240:241], v146 offset:27936
	ds_read2_b32 v[244:245], v185 offset1:1
	s_add_i32 s4, s26, 32
	s_add_i32 s5, s26, 0xffffff20
	s_add_i32 s6, s27, 64
	s_add_i32 s7, s27, 0xfffff840
	v_cvt_pk_bf16_f32 v192, v76, s0
	v_cvt_pk_bf16_f32 v193, v77, s0
	v_cvt_pk_bf16_f32 v194, v78, s0
	v_cvt_pk_bf16_f32 v195, v79, s0
	v_cvt_pk_bf16_f32 v196, v80, s0
	v_cvt_pk_bf16_f32 v197, v81, s0
	v_cvt_pk_bf16_f32 v198, v82, s0
	v_cvt_pk_bf16_f32 v199, v83, s0
	s_and_b64 s[2:3], s[0:1], exec
	s_cselect_b32 s2, s4, s7
	s_waitcnt lgkmcnt(11)
	v_mfma_f32_16x16x32_bf16 v[92:95], v[96:99], v[208:211], v[92:95]
	ds_read2_b32 v[246:247], v184 offset1:1
	v_perm_b32 v190, v197, v196, s25
	v_perm_b32 v189, v195, v194, s25
	v_perm_b32 v188, v193, v192, s25
	v_perm_b32 v191, v199, v198, s25
	s_add_i32 s4, s2, s22
	s_and_b64 s[2:3], s[0:1], exec
	s_cselect_b32 s2, s5, s6
	s_add_i32 s2, s2, s21
	s_cmp_lt_u32 s24, 5
	s_waitcnt lgkmcnt(11)
	v_mfma_f32_16x16x32_bf16 v[92:95], v[188:191], v[212:215], v[92:95]
	ds_read_b64_tr_b16 v[248:249], v146 offset:27968
	s_cselect_b32 s2, s4, s2
	s_ashr_i32 s3, s2, 31
	s_lshl_b64 s[36:37], s[2:3], 10
	s_nop 3
	v_cvt_pk_bf16_f32 v92, v92, v93
	v_cvt_pk_bf16_f32 v93, v94, v95
	v_lshl_add_u64 v[94:95], v[100:101], 0, s[36:37]
	global_store_dwordx2 v[94:95], v[92:93], off
	s_waitcnt lgkmcnt(10)
	v_mfma_f32_16x16x32_bf16 v[92:95], v[200:203], v[224:227], 0
	ds_read_b64_tr_b16 v[250:251], v147 offset:27968
	ds_read2_b32 v[204:205], v164 offset1:1
	v_mfma_f32_16x16x32_bf16 v[92:95], v[96:99], v[216:219], v[92:95]
	s_waitcnt lgkmcnt(11)
	v_mfma_f32_16x16x32_bf16 v[92:95], v[188:191], v[228:231], v[92:95]
	ds_read2_b32 v[206:207], v165 offset1:1
	s_nop 7
	v_cvt_pk_bf16_f32 v92, v92, v93
	v_cvt_pk_bf16_f32 v93, v94, v95
	v_lshl_add_u64 v[94:95], v[102:103], 0, s[36:37]
	global_store_dwordx2 v[94:95], v[92:93], off
	s_waitcnt lgkmcnt(11)
	v_pk_mul_f32 v[88:89], v[88:89], v[232:233]
	ds_read_b64_tr_b16 v[208:209], v146 offset:28000
	s_waitcnt lgkmcnt(11)
	v_pk_mul_f32 v[90:91], v[90:91], v[234:235]
	ds_read_b64_tr_b16 v[210:211], v147 offset:28000
	s_waitcnt lgkmcnt(9)
	v_mfma_f32_16x16x32_bf16 v[88:91], v[236:239], v[200:203], v[88:91]
	ds_read2_b32 v[212:213], v187 offset1:1
	ds_read2_b32 v[214:215], v186 offset1:1
	s_waitcnt lgkmcnt(9)
	v_pk_mul_f32 v[72:73], v[72:73], v[244:245]
	s_waitcnt lgkmcnt(8)
	v_pk_mul_f32 v[74:75], v[74:75], v[246:247]
	s_nop 1
	v_mfma_f32_16x16x32_bf16 v[72:75], v[240:243], v[200:203], v[72:75]
	s_waitcnt lgkmcnt(5)
	v_pk_mul_f32 v[76:77], v[76:77], v[204:205]
	s_waitcnt lgkmcnt(4)
	v_pk_mul_f32 v[78:79], v[78:79], v[206:207]
	s_nop 1
	v_mfma_f32_16x16x32_bf16 v[76:79], v[248:251], v[200:203], v[76:79]
	s_waitcnt vmcnt(11)
	ds_write_b128 v121, v[48:51] offset:11776
	s_waitcnt vmcnt(10)
	ds_write_b128 v122, v[56:59]
	s_waitcnt lgkmcnt(3)
	v_pk_mul_f32 v[80:81], v[80:81], v[212:213]
	s_waitcnt lgkmcnt(2)
	v_pk_mul_f32 v[82:83], v[82:83], v[214:215]
	s_nop 1
	v_mfma_f32_16x16x32_bf16 v[84:87], v[208:211], v[200:203], v[80:83]
	s_waitcnt lgkmcnt(0)
	s_and_saveexec_b64 s[36:37], s[38:39]
	ds_write_b128 v148, v[52:55]
	s_or_b64 exec, exec, s[36:37]
	s_and_saveexec_b64 s[36:37], s[40:41]
	ds_write_b32 v149, v119 offset:19968
	s_or_b64 exec, exec, s[36:37]
	s_cmp_gt_u32 s24, 61
	s_waitcnt lgkmcnt(0)
	s_barrier
	s_cbranch_scc1 .LBB0_630
	v_add_u32_e32 v48, 0x100, v150
	s_movk_i32 s2, 0x100
	v_cmp_gt_i32_e32 vcc, s2, v48
	v_mov_b32_e32 v50, s21
	v_mov_b32_e32 v51, s22
	v_cndmask_b32_e32 v49, v174, v175, vcc
	v_add3_u32 v49, v132, v49, s27
	v_cndmask_b32_e32 v48, v150, v48, vcc
	v_add_u32_e32 v49, 0xfffff661, v49
	v_cndmask_b32_e32 v50, v50, v51, vcc
	v_cndmask_b32_e64 v48, v49, v48, s[0:1]
	v_add_u32_e32 v48, v48, v50
	s_movk_i32 s2, 0x3800
	v_add_co_u32_e32 v56, vcc, 0xa000, v112
	v_mad_i64_i32 v[48:49], s[2:3], v48, s2, v[104:105]
	s_nop 0
	v_addc_co_u32_e32 v57, vcc, 0, v113, vcc
	global_load_dwordx4 v[48:51], v[48:49], off offset:1024
	s_nop 0
	global_load_dwordx4 v[56:59], v[56:57], off nt
	s_and_saveexec_b64 s[36:37], s[38:39]
	s_cbranch_execz .LBB0_627
	v_lshl_add_u64 v[52:53], v[106:107], 0, s[44:45]
	v_add_co_u32_e32 v52, vcc, 0x12841000, v52
	s_nop 1
	v_addc_co_u32_e32 v53, vcc, 0, v53, vcc
	global_load_dwordx4 v[52:55], v[52:53], off nt

; DI void gla_scan_item(const P& p, int seq, unsigned char* smem) {
;     ...
;     auto storel = [&](const GlaRegs& R, int buf) {
;         unsigned char* base = smem + buf * BUFB;
;         bf16_t* sat = (bf16_t*)base; bf16_t* sqt = (bf16_t*)(base + 2560); bf16_t* sko = (bf16_t*)(base + 2560 + 4608); bf16_t* sv = (bf16_t*)(base + 2560 + 9216); float* sdc = (float*)(base + 2560 + 9216 + 8704);
;         { const int pos = tid >> 4, ch = tid & 15; *(u32x4*)(sv + pos * 136 + 8 * ch) = R.rv; }
;         { const int t2 = tid & 255, pos = t2 >> 3, ch = t2 & 7; *(u32x4*)((tid < 256 ? sqt : sko) + pos * 72 + 8 * ch) = R.rq; }
;         if (tid < 128) { const int i = tid >> 2, ch = tid & 3; *(u32x4*)(sat + i * 40 + 8 * ch) = R.ra; }
;     ...
;     auto compute = [&](int c) {
;         const unsigned char* base = smem + (c & 1) * BUFB;
;         const bf16_t* sat = (const bf16_t*)base; const bf16_t* sqt = (const bf16_t*)(base + 2560); const bf16_t* sko = (const bf16_t*)(base + 2560 + 4608); const bf16_t* sv = (const bf16_t*)(base + 2560 + 9216); const float* sdc = (const float*)(base + 2560 + 9216 + 8704);
;         const int dv0 = 16 * w;
;         const bf16x8 vb = tr2(sv + (8 * g + q4) * 136 + dv0 + 4 * p4, sv + (8 * g + 4 + q4) * 136 + dv0 + 4 * p4);
;         bf16x8 bs[2];
;         bs[0] = packacc(st[0], st[1]); bs[1] = packacc(st[2], st[3]);
; #pragma unroll
;         for (int mt = 0; mt < 2; ++mt) {
;             f32x4 acc = (f32x4){0.f, 0.f, 0.f, 0.f};
;             acc = mfma16(vb, ld8(sat + (16 * mt + l15) * 40 + 8 * g), acc);
; #pragma unroll
;             for (int ks = 0; ks < 2; ++ks) {
;                 const bf16_t* r0 = sqt + (16 * mt + l15) * 72 + 32 * ks + 4 * g;
;                 acc = mfma16(bs[ks], ld4x2(r0, r0 + 16), acc);
;             }
;             bf16_t* ob = OG + (size_t)prow(b, dir, 32 * c) * 512 + 128 * h;
;             u32x2 ov; ov.x = pk2(acc[0], acc[1]); ov.y = pk2(acc[2], acc[3]);
;             *(u32x2*)(ob + sgn * ((16 * mt + l15) * 512) + dv0 + 4 * g) = ov;
;         }
; #pragma unroll
;         for (int dt = 0; dt < 4; ++dt) {
;             const bf16x8 ak = tr2(sko + (8 * g + q4) * 72 + 16 * dt + 4 * p4, sko + (8 * g + 4 + q4) * 72 + 16 * dt + 4 * p4);
; #pragma unroll
;             for (int r = 0; r < 4; ++r) st[dt][r] *= sdc[16 * dt + 4 * g + r];
;             st[dt] = mfma16(ak, vb, st[dt]);
;         }
;     };
.LBB0_630:
	ds_read_b64_tr_b16 v[200:201], v123 offset:11776
	ds_read_b64_tr_b16 v[202:203], v124 offset:11776
	ds_read_b128 v[204:207], v125
	ds_read2_b64 v[208:211], v152 offset0:64 offset1:68
	ds_read2_b64 v[212:215], v152 offset0:72 offset1:76
	ds_read2_b64 v[216:219], v151 offset0:64 offset1:68
	ds_read_b128 v[224:227], v127
	ds_read2_b64 v[228:231], v151 offset0:72 offset1:76
	ds_read2_b32 v[232:233], v153 offset1:1
	ds_read2_b32 v[234:235], v156 offset1:1
	ds_read_b64_tr_b16 v[238:239], v144 offset:7168
	ds_read_b64_tr_b16 v[242:243], v144 offset:7200
	v_cvt_pk_bf16_f32 v92, v88, s0
	v_cvt_pk_bf16_f32 v95, v89, s0
	v_cvt_pk_bf16_f32 v93, v90, s0
	v_cvt_pk_bf16_f32 v134, v91, s0
	v_cvt_pk_bf16_f32 v94, v72, s0
	v_cvt_pk_bf16_f32 v135, v73, s0
	v_cvt_pk_bf16_f32 v188, v74, s0
	v_cvt_pk_bf16_f32 v189, v75, s0
	v_perm_b32 v94, v135, v94, s25
	v_perm_b32 v93, v134, v93, s25
	v_perm_b32 v92, v95, v92, s25
	v_perm_b32 v95, v189, v188, s25
	s_waitcnt lgkmcnt(9)
	v_mfma_f32_16x16x32_bf16 v[80:83], v[200:203], v[204:207], 0
	ds_read_b64_tr_b16 v[236:237], v143 offset:7168
	ds_read_b64_tr_b16 v[240:241], v143 offset:7200
	ds_read2_b32 v[244:245], v158 offset1:1
	s_add_i32 s4, s26, 64
	s_add_i32 s5, s26, 0xffffff40
	s_add_i32 s6, s27, 32
	s_add_i32 s7, s27, 0xfffff820
	v_cvt_pk_bf16_f32 v192, v76, s0
	v_cvt_pk_bf16_f32 v193, v77, s0
	v_cvt_pk_bf16_f32 v194, v78, s0
	v_cvt_pk_bf16_f32 v195, v79, s0
	v_cvt_pk_bf16_f32 v196, v84, s0
	v_cvt_pk_bf16_f32 v197, v85, s0
	v_cvt_pk_bf16_f32 v198, v86, s0
	v_cvt_pk_bf16_f32 v199, v87, s0
	s_and_b64 s[2:3], s[0:1], exec
	s_cselect_b32 s2, s4, s7
	s_waitcnt lgkmcnt(11)
	v_mfma_f32_16x16x32_bf16 v[80:83], v[92:95], v[208:211], v[80:83]
	ds_read2_b32 v[246:247], v157 offset1:1
	v_perm_b32 v190, v197, v196, s25
	v_perm_b32 v189, v195, v194, s25
	v_perm_b32 v188, v193, v192, s25
	v_perm_b32 v191, v199, v198, s25
	s_add_i32 s4, s2, s22
	s_and_b64 s[2:3], s[0:1], exec
	s_cselect_b32 s2, s5, s6
	s_add_i32 s2, s2, s21
	s_cmp_lt_u32 s24, 4
	s_waitcnt lgkmcnt(11)
	v_mfma_f32_16x16x32_bf16 v[80:83], v[188:191], v[212:215], v[80:83]
	ds_read_b64_tr_b16 v[248:249], v143 offset:7232
	s_cselect_b32 s2, s4, s2
	s_ashr_i32 s3, s2, 31
	s_lshl_b64 s[36:37], s[2:3], 10
	s_nop 3
	v_cvt_pk_bf16_f32 v80, v80, v81
	v_cvt_pk_bf16_f32 v81, v82, v83
	v_lshl_add_u64 v[82:83], v[100:101], 0, s[36:37]
	global_store_dwordx2 v[82:83], v[80:81], off
	s_waitcnt lgkmcnt(10)
	v_mfma_f32_16x16x32_bf16 v[80:83], v[200:203], v[224:227], 0
	ds_read_b64_tr_b16 v[250:251], v144 offset:7232
	ds_read2_b32 v[204:205], v154 offset1:1
	v_mfma_f32_16x16x32_bf16 v[80:83], v[92:95], v[216:219], v[80:83]
	s_waitcnt lgkmcnt(11)
	v_mfma_f32_16x16x32_bf16 v[80:83], v[188:191], v[228:231], v[80:83]
	ds_read2_b32 v[206:207], v155 offset1:1
	s_nop 7
	v_cvt_pk_bf16_f32 v80, v80, v81
	v_cvt_pk_bf16_f32 v81, v82, v83
	v_lshl_add_u64 v[82:83], v[102:103], 0, s[36:37]
	global_store_dwordx2 v[82:83], v[80:81], off
	s_waitcnt lgkmcnt(11)
	v_pk_mul_f32 v[80:81], v[88:89], v[232:233]
	ds_read_b64_tr_b16 v[208:209], v143 offset:7264
	s_waitcnt lgkmcnt(11)
	v_pk_mul_f32 v[82:83], v[90:91], v[234:235]
	ds_read_b64_tr_b16 v[210:211], v144 offset:7264
	s_waitcnt lgkmcnt(9)
	v_mfma_f32_16x16x32_bf16 v[92:95], v[236:239], v[200:203], v[80:83]
	ds_read2_b32 v[212:213], v161 offset1:1
	ds_read2_b32 v[214:215], v160 offset1:1
	s_nop 2
	s_waitcnt lgkmcnt(9)
	v_pk_mul_f32 v[72:73], v[72:73], v[244:245]
	s_waitcnt lgkmcnt(8)
	v_pk_mul_f32 v[74:75], v[74:75], v[246:247]
	s_nop 1
	v_mfma_f32_16x16x32_bf16 v[72:75], v[240:243], v[200:203], v[72:75]
	s_waitcnt lgkmcnt(5)
	v_pk_mul_f32 v[76:77], v[76:77], v[204:205]
	s_waitcnt lgkmcnt(4)
	v_pk_mul_f32 v[78:79], v[78:79], v[206:207]
	s_nop 1
	v_mfma_f32_16x16x32_bf16 v[80:83], v[248:251], v[200:203], v[76:79]
	s_nop 2
	s_waitcnt vmcnt(11)
	ds_write_b128 v121, v[60:63] offset:32512
	s_waitcnt vmcnt(10)
	ds_write_b128 v122, v[68:71] offset:20736
	s_waitcnt lgkmcnt(3)
	v_pk_mul_f32 v[84:85], v[84:85], v[212:213]
	s_waitcnt lgkmcnt(2)
	v_pk_mul_f32 v[86:87], v[86:87], v[214:215]
	s_nop 1
	v_mfma_f32_16x16x32_bf16 v[88:91], v[208:211], v[200:203], v[84:87]
	s_waitcnt lgkmcnt(0)
	s_and_saveexec_b64 s[36:37], s[38:39]
	ds_write_b128 v148, v[64:67] offset:20736
	s_or_b64 exec, exec, s[36:37]
	s_and_saveexec_b64 s[36:37], s[40:41]
	ds_write_b32 v149, v120 offset:40704
	s_or_b64 exec, exec, s[36:37]
	s_cmp_gt_u32 s24, 60
	s_waitcnt lgkmcnt(0)
	s_barrier
	s_cbranch_scc1 .LBB0_579
	v_add_u32_e32 v60, 0x120, v150
	s_movk_i32 s2, 0x100
	v_cmp_gt_i32_e32 vcc, s2, v60
	v_add_u32_e32 v61, 32, v150
	v_mov_b32_e32 v63, s22
	v_cndmask_b32_e32 v62, v174, v175, vcc
	v_add3_u32 v62, v132, v62, s27
	v_cndmask_b32_e32 v60, v61, v60, vcc
	v_mov_b32_e32 v61, s21
	v_add_u32_e32 v62, 0xfffff641, v62
	v_cndmask_b32_e32 v61, v61, v63, vcc
	v_cndmask_b32_e64 v60, v62, v60, s[0:1]
	v_add_u32_e32 v60, v60, v61
	s_movk_i32 s2, 0x3800
	v_add_co_u32_e32 v68, vcc, 0xb000, v112
	v_mad_i64_i32 v[60:61], s[2:3], v60, s2, v[104:105]
	s_nop 0
	v_addc_co_u32_e32 v69, vcc, 0, v113, vcc
	global_load_dwordx4 v[60:63], v[60:61], off offset:1024
	s_nop 0
	global_load_dwordx4 v[68:71], v[68:69], off nt
	s_and_saveexec_b64 s[36:37], s[38:39]
	s_cbranch_execz .LBB0_637
	v_lshl_add_u64 v[64:65], v[106:107], 0, s[44:45]
	v_add_co_u32_e32 v64, vcc, 0x12841000, v64
	s_nop 1
	v_addc_co_u32_e32 v65, vcc, 0, v65, vcc
	global_load_dwordx4 v[64:67], v[64:65], off offset:2048 nt
